# GLA loops: next-unit prefetch no longer waited for right after issue (loads land in carried registers, conservative waits removed)
# baseline (speedup 1.0000x reference)
; #define LAS __attribute__((address_space(3)))
; __global__ void __launch_bounds__(NWAVES * 64, 2) hymba_fwd(Args args) {
;     ...
;     { gla::GPre cur, nxt; int u = bid;
;       if (u < NCHUNK * 4) gla::load_pre<false>(cur, PROJ, args, WGT, STATE, u >> 2, u & 3);
;       for (; u < NCHUNK * 4; u += G) { const int un = u + G;
;         if (un < NCHUNK * 4) gla::load_pre<false>(nxt, PROJ, args, WGT, STATE, un >> 2, un & 3);
;         gla::g1_unit(cur, STATE, DEC, u >> 2, u & 3, (LAS char*)ldsl); cur = nxt; } }
.LBB0_196:
	v_cndmask_b32_e64 v32, 0, 1, s[0:1]
	v_cmp_ne_u32_e64 s[6:7], 1, v32
	s_add_u32 s4, s70, 0x1c000000
	s_addc_u32 s5, s71, 0
	v_writelane_b32 v255, s6, 15
	s_andn2_b64 vcc, exec, s[0:1]
	s_nop 0
	v_writelane_b32 v255, s7, 16
	s_cbranch_vccnz .LBB0_233
	s_add_i32 s0, s2, s74
	s_lshl_b32 s3, s0, 4
	s_lshl_b32 s15, s74, 4
	s_movk_i32 s25, 0x1a00
	s_mov_b32 s7, 0
	v_mov_b32_e32 v81, 0
	s_mov_b64 s[10:11], 0x1000
	s_movk_i32 s35, 0x1800
	s_movk_i32 s58, 0x110
	s_mov_b32 s59, 0xbfb8aa3b
	s_mov_b32 s14, 0x3f317218
	s_mov_b32 s24, 0x3db8aa3b
	s_mov_b32 s64, 0xffff0000
	s_movk_i32 s65, 0x7fff
	s_movk_i32 s72, 0x90
	v_mbcnt_hi_u32_b32 v125, -1, v124
	v_mov_b32_e32 v126, 0x900
	v_mov_b32_e32 v127, 0x1200
	v_mov_b32_e32 v128, 0x1b00
	s_mov_b32 s30, s2
	s_waitcnt vmcnt(0)
	s_branch .LBB0_199

; __device__ __forceinline__ int crow(int r, int hi) { return (r & 3) + 8 * (r >> 2) + 4 * hi; }
; template <bool G3>
; __device__ __forceinline__ void load_pre(GPre& R, const bf16* __restrict__ P, const Args& a, const bf16* __restrict__ WGT, const bf16* __restrict__ STATE, int n, int h) {
;   int tid_ = threadIdx.x; asm volatile("" : "+v"(tid_)); const int tid = tid_, lane = tid & 63, wid = __builtin_amdgcn_readfirstlane(tid >> 6), r32 = lane & 31, hi = lane >> 5, row0 = n * 64, s = tid >> 3, dg = tid & 7;
;   R.kk = *(const v4u*)(P + (size_t)(row0 + s) * LDP + C_GK + h * 64 + dg * 8);
;   if (G3) { R.qq = *(const v4u*)(P + (size_t)(row0 + s) * LDP + C_GQ + h * 64 + dg * 8);
;     const int ct_ = wid >> 2, et_ = wid & 3;
; #pragma unroll
;     for (int r = 0; r < 16; ++r) R.grv[r] = P[(size_t)(row0 + 32 * ct_ + crow(r, hi)) * LDP + C_GR + h * 128 + 32 * et_ + r32]; }
;   if (wid < 4) { const int dir = wid >> 1, dt = wid & 1, c = h * 64 + 32 * dt + r32;
;     R.wb = *(const bf16x8*)(WGT + ((size_t)dir * 256 + c) * 16 + 8 * hi); R.bias = (dir ? a.in[14] : a.in[12])[c];
;     R.lr0 = *(const bf16x8*)(P + (size_t)(row0 + r32) * LDP + (dir ? C_LRB : C_LRF) + 8 * hi); R.lr1 = *(const bf16x8*)(P + (size_t)(row0 + 32 + r32) * LDP + (dir ? C_LRB : C_LRF) + 8 * hi);
;   } else { const int t = tid - 256, s2 = t >> 2, part = t & 3;
;     { const v4u* src = (const v4u*)(P + (size_t)(row0 + s2) * LDP + C_GV + h * 128 + part * 32); R.vv[0] = src[0]; R.vv[1] = src[1]; R.vv[2] = src[2]; R.vv[3] = src[3]; }
.LBB0_199:
	s_add_i32 s73, s30, s74
	s_cmpk_gt_i32 s73, 0xbff
	s_cselect_b64 s[26:27], -1, 0
	s_and_b64 vcc, exec, s[26:27]
	s_cbranch_vccnz .LBB0_205
	v_mov_b32_e32 v82, v210
	s_and_b32 s28, s3, 0xffffffc0
	v_ashrrev_i32_e32 v52, 3, v82
	s_and_b32 s31, s73, 3
	v_add_u32_e32 v54, s28, v52
	v_mov_b64_e32 v[52:53], s[44:45]
	v_mad_i64_i32 v[52:53], s[0:1], v54, s25, v[52:53]
	s_lshl_b32 s6, s31, 7
	v_lshlrev_b32_e32 v54, 4, v82
	v_lshl_add_u64 v[52:53], v[52:53], 0, s[6:7]
	v_and_b32_e32 v80, 0x70, v54
	v_lshl_add_u64 v[52:53], v[52:53], 0, v[80:81]
	global_load_dwordx4 v[52:55], v[52:53], off offset:3584
	v_readfirstlane_b32 s29, v82
	s_ashr_i32 s33, s29, 6
	s_cmp_gt_i32 s33, 3
	s_mov_b64 s[0:1], -1
	s_cbranch_scc0 .LBB0_202
	v_add_u32_e32 v64, 0xffffff00, v82
	v_ashrrev_i32_e32 v64, 2, v64
	v_add_u32_e32 v66, s28, v64
	v_mov_b64_e32 v[64:65], s[44:45]
	v_mad_i64_i32 v[64:65], s[0:1], v66, s25, v[64:65]
	s_lshl_b32 s6, s31, 8
	v_lshlrev_b32_e32 v66, 6, v82
	v_lshl_add_u64 v[64:65], v[64:65], 0, s[6:7]
	v_and_b32_e32 v80, 0xc0, v66
	v_lshl_add_u64 v[64:65], v[64:65], 0, v[80:81]
	v_lshl_add_u64 v[72:73], v[64:65], 0, s[10:11]
	v_add_co_u32_e32 v64, vcc, 0x1000, v64
	s_mov_b64 s[0:1], 0
	s_nop 0
	v_addc_co_u32_e32 v65, vcc, 0, v65, vcc
	global_load_dwordx4 v[32:35], v[64:65], off
	s_nop 0
	global_load_dwordx4 v[44:47], v[72:73], off offset:48
	global_load_dwordx4 v[40:43], v[72:73], off offset:32
	s_nop 0
	global_load_dwordx4 v[36:39], v[72:73], off offset:16

; #define LAS __attribute__((address_space(3)))
; __device__ __forceinline__ float logsig(float z) { return fminf(z, 0.f) - 0.6931471805599453f * __builtin_amdgcn_logf(1.0f + __builtin_amdgcn_exp2f(-1.4426950408889634f * __builtin_fabsf(z))); }
; template <bool WITH_S>
; __device__ __forceinline__ void prep(const GPre& R, int n, int h, LAS char* lds) {
;     ...
;   if (wid < 4) {
;     const int dir = wid >> 1, dt = wid & 1;
;     const bf16x8 bfr = R.wb;
;     const float bias = R.bias;
;     float g[32];
; #pragma unroll
;     for (int st = 0; st < 2; ++st) { const bf16x8 afr = st ? R.lr1 : R.lr0;
;       f32x16 z = {}; z = __builtin_amdgcn_mfma_f32_32x32x16_bf16(afr, bfr, z, 0, 0, 0);
; #pragma unroll
;       for (int r = 0; r < 16; ++r) g[16 * st + r] = logsig(z[r] + bias) * (0.0625f * 1.4426950408889634f); }
;     ...
;     { LAS v4u* dst = (LAS v4u*)(lds + L_V + s * VS + part * 64); dst[0] = R.vv[0]; dst[1] = R.vv[1]; dst[2] = R.vv[2]; dst[3] = R.vv[3]; }
.LBB0_204:
.LBB0_205:
	v_mov_b32_e32 v80, v210
	v_mov_b32_e32 v131, v210
	s_mov_b64 s[0:1], -1
	v_readfirstlane_b32 s33, v131
	s_ashr_i32 s31, s33, 6
	v_readfirstlane_b32 s6, v80
	s_cmp_gt_i32 s31, 3
	s_cbranch_scc0 .LBB0_207
	v_add_u32_e32 v64, 0xffffff00, v131
	v_lshrrev_b32_e32 v64, 2, v64
	v_lshlrev_b32_e32 v65, 6, v131
	v_mul_lo_u32 v64, v64, s58
	v_and_b32_e32 v65, 0xc0, v65
	v_add3_u32 v64, 0, v64, v65
	ds_write_b128 v64, v[12:15] offset:34816
	ds_write_b128 v64, v[8:11] offset:34832
	ds_write_b128 v64, v[4:7] offset:34848
	ds_write_b128 v64, v[0:3] offset:34864
	s_mov_b64 s[0:1], 0
.LBB0_207:
	s_andn2_b64 vcc, exec, s[0:1]
	s_cbranch_vccnz .LBB0_217
	v_mfma_f32_32x32x16_bf16 v[0:15], v[28:31], v[20:23], 0
	s_cmpk_gt_u32 s33, 0x7f
	s_cselect_b64 s[28:29], -1, 0
	s_cmpk_lt_u32 s33, 0x80
	s_mov_b64 s[0:1], -1
	s_nop 7
	v_add_f32_e32 v1, v84, v1
	v_add_f32_e32 v29, v84, v2
	v_min_f32_e32 v2, 0, v1
	v_mul_f32_e64 v1, |v1|, s59
	v_exp_f32_e32 v1, v1
	v_add_f32_e32 v28, v84, v0
	v_min_f32_e32 v0, 0, v28
	v_mul_f32_e64 v28, |v28|, s59
	v_exp_f32_e32 v30, v28
	v_min_f32_e32 v28, 0, v29
	v_mul_f32_e64 v29, |v29|, s59
	v_add_f32_e32 v1, 1.0, v1
	v_add_f32_e32 v3, v84, v3
	v_log_f32_e32 v64, v1
	v_exp_f32_e32 v1, v29
	v_mul_f32_e64 v29, |v3|, s59
	v_exp_f32_e32 v29, v29
	v_min_f32_e32 v68, 0, v3
	v_add_f32_e32 v1, 1.0, v1
	v_log_f32_e32 v66, v1
	v_add_f32_e32 v1, 1.0, v29
	v_add_f32_e32 v3, v84, v4
	v_log_f32_e32 v70, v1
	v_min_f32_e32 v1, 0, v3
	v_mul_f32_e64 v3, |v3|, s59
	v_add_f32_e32 v4, v84, v5
	v_exp_f32_e32 v3, v3
	v_mul_f32_e64 v5, |v4|, s59
	v_exp_f32_e32 v5, v5
	v_add_f32_e32 v30, 1.0, v30
	v_add_f32_e32 v3, 1.0, v3
	v_log_f32_e32 v31, v3
	v_min_f32_e32 v3, 0, v4
	v_add_f32_e32 v4, 1.0, v5
	v_log_f32_e32 v65, v4
	v_add_f32_e32 v4, v84, v6
	v_min_f32_e32 v29, 0, v4
	v_mul_f32_e64 v4, |v4|, s59
	v_add_f32_e32 v5, v84, v7
	v_exp_f32_e32 v4, v4
	v_mul_f32_e64 v6, |v5|, s59
	v_exp_f32_e32 v6, v6
	v_log_f32_e32 v30, v30
	v_add_f32_e32 v4, 1.0, v4
	v_log_f32_e32 v67, v4
	v_add_f32_e32 v4, 1.0, v6
	v_log_f32_e32 v71, v4
	v_pk_fma_f32 v[0:1], v[30:31], s[14:15], v[0:1] op_sel_hi:[1,0,1] neg_lo:[1,0,0] neg_hi:[1,0,0]
	v_min_f32_e32 v69, 0, v5
	v_pk_mul_f32 v[74:75], v[0:1], s[24:25] op_sel_hi:[1,0]
	v_pk_fma_f32 v[0:1], v[64:65], s[14:15], v[2:3] op_sel_hi:[1,0,1] neg_lo:[1,0,0] neg_hi:[1,0,0]
	v_add_f32_e32 v3, v84, v9
	v_pk_mul_f32 v[78:79], v[0:1], s[24:25] op_sel_hi:[1,0]
	v_pk_fma_f32 v[0:1], v[66:67], s[14:15], v[28:29] op_sel_hi:[1,0,1] neg_lo:[1,0,0] neg_hi:[1,0,0]
	v_mul_f32_e64 v2, |v3|, s59
	v_pk_mul_f32 v[82:83], v[0:1], s[24:25] op_sel_hi:[1,0]
	v_pk_fma_f32 v[0:1], v[70:71], s[14:15], v[68:69] op_sel_hi:[1,0,1] neg_lo:[1,0,0] neg_hi:[1,0,0]
	v_exp_f32_e32 v5, v2
	v_pk_mul_f32 v[28:29], v[0:1], s[24:25] op_sel_hi:[1,0]
	v_add_f32_e32 v1, v84, v8
	v_min_f32_e32 v0, 0, v1
	v_mul_f32_e64 v1, |v1|, s59
	v_exp_f32_e32 v1, v1
	v_min_f32_e32 v4, 0, v3
	v_add_f32_e32 v3, v84, v11
	v_min_f32_e32 v30, 0, v3
	v_add_f32_e32 v1, 1.0, v1
	v_log_f32_e32 v2, v1
	v_add_f32_e32 v1, 1.0, v5
	v_log_f32_e32 v6, v1
	v_add_f32_e32 v1, v84, v10
	v_min_f32_e32 v8, 0, v1
	v_mul_f32_e64 v1, |v1|, s59
	v_exp_f32_e32 v1, v1
	v_mul_f32_e64 v5, |v3|, s59
	v_exp_f32_e32 v5, v5
	v_add_f32_e32 v3, v84, v12
	v_add_f32_e32 v1, 1.0, v1
	v_log_f32_e32 v10, v1
	v_add_f32_e32 v1, 1.0, v5
	v_log_f32_e32 v64, v1
	v_min_f32_e32 v1, 0, v3
	v_mul_f32_e64 v3, |v3|, s59
	v_add_f32_e32 v5, v84, v13
	v_exp_f32_e32 v3, v3
	v_mul_f32_e64 v7, |v5|, s59
	v_add_f32_e32 v11, v84, v14
	v_exp_f32_e32 v7, v7
	v_min_f32_e32 v9, 0, v11
	v_mul_f32_e64 v11, |v11|, s59
	v_add_f32_e32 v12, v84, v15
	v_exp_f32_e32 v11, v11
	v_mul_f32_e64 v13, |v12|, s59
	v_exp_f32_e32 v13, v13
	v_add_f32_e32 v3, 1.0, v3
	v_log_f32_e32 v3, v3
	v_add_f32_e32 v7, 1.0, v7
	v_log_f32_e32 v7, v7
	v_add_f32_e32 v11, 1.0, v11
	v_log_f32_e32 v11, v11
	v_min_f32_e32 v31, 0, v12
	v_add_f32_e32 v12, 1.0, v13
	v_log_f32_e32 v65, v12
	v_min_f32_e32 v5, 0, v5
	v_pk_fma_f32 v[0:1], v[2:3], s[14:15], v[0:1] op_sel_hi:[1,0,1] neg_lo:[1,0,0] neg_hi:[1,0,0]
	s_nop 0
	v_pk_mul_f32 v[86:87], v[0:1], s[24:25] op_sel_hi:[1,0]
	v_pk_fma_f32 v[0:1], v[6:7], s[14:15], v[4:5] op_sel_hi:[1,0,1] neg_lo:[1,0,0] neg_hi:[1,0,0]
	s_nop 0
	v_pk_mul_f32 v[88:89], v[0:1], s[24:25] op_sel_hi:[1,0]
	v_pk_fma_f32 v[0:1], v[10:11], s[14:15], v[8:9] op_sel_hi:[1,0,1] neg_lo:[1,0,0] neg_hi:[1,0,0]
	s_nop 0
	v_pk_mul_f32 v[90:91], v[0:1], s[24:25] op_sel_hi:[1,0]
	v_pk_fma_f32 v[0:1], v[64:65], s[14:15], v[30:31] op_sel_hi:[1,0,1] neg_lo:[1,0,0] neg_hi:[1,0,0]
	s_nop 0
; __device__ __forceinline__ float logsig(float z) { return fminf(z, 0.f) - 0.6931471805599453f * __builtin_amdgcn_logf(1.0f + __builtin_amdgcn_exp2f(-1.4426950408889634f * __builtin_fabsf(z))); }
; template <bool WITH_S>
; __device__ __forceinline__ void prep(const GPre& R, int n, int h, LAS char* lds) {
;     ...
;     for (int st = 0; st < 2; ++st) { const bf16x8 afr = st ? R.lr1 : R.lr0;
;       f32x16 z = {}; z = __builtin_amdgcn_mfma_f32_32x32x16_bf16(afr, bfr, z, 0, 0, 0);
; #pragma unroll
;       for (int r = 0; r < 16; ++r) g[16 * st + r] = logsig(z[r] + bias) * (0.0625f * 1.4426950408889634f); }
;     float T[8], Tp[8];
;     if (dir == 0) {
; #pragma unroll
;       for (int i = 0; i < 8; ++i) { g[4 * i + 1] += g[4 * i]; g[4 * i + 2] += g[4 * i + 1]; g[4 * i + 3] += g[4 * i + 2]; T[i] = g[4 * i + 3]; }
;     } else {
; #pragma unroll
;       for (int i = 0; i < 8; ++i) { g[4 * i + 2] += g[4 * i + 3]; g[4 * i + 1] += g[4 * i + 2]; g[4 * i] += g[4 * i + 1]; T[i] = g[4 * i]; }
;     }
	v_pk_mul_f32 v[30:31], v[0:1], s[24:25] op_sel_hi:[1,0]
	v_mfma_f32_32x32x16_bf16 v[0:15], v[24:27], v[20:23], 0
	s_nop 11
	v_add_f32_e32 v1, v84, v1
	v_mul_f32_e64 v21, |v1|, s59
	v_exp_f32_e32 v21, v21
	v_min_f32_e32 v22, 0, v1
	v_add_f32_e32 v3, v84, v3
	v_min_f32_e32 v64, 0, v3
	v_add_f32_e32 v1, 1.0, v21
	v_log_f32_e32 v24, v1
	v_add_f32_e32 v1, v84, v2
	v_min_f32_e32 v2, 0, v1
	v_mul_f32_e64 v1, |v1|, s59
	v_exp_f32_e32 v1, v1
	v_mul_f32_e64 v21, |v3|, s59
	v_exp_f32_e32 v21, v21
	v_add_f32_e32 v3, v84, v4
	v_add_f32_e32 v1, 1.0, v1
	v_log_f32_e32 v26, v1
	v_add_f32_e32 v1, 1.0, v21
	v_log_f32_e32 v66, v1
	v_min_f32_e32 v1, 0, v3
	v_mul_f32_e64 v3, |v3|, s59
	v_add_f32_e32 v4, v84, v5
	v_exp_f32_e32 v3, v3
	v_mul_f32_e64 v5, |v4|, s59
	v_exp_f32_e32 v5, v5
	v_add_f32_e32 v20, v84, v0
	v_min_f32_e32 v0, 0, v20
	v_mul_f32_e64 v20, |v20|, s59
	v_add_f32_e32 v3, 1.0, v3
	v_exp_f32_e32 v20, v20
	v_log_f32_e32 v21, v3
	v_min_f32_e32 v23, 0, v4
	v_add_f32_e32 v3, 1.0, v5
	v_add_f32_e32 v4, v84, v6
	v_log_f32_e32 v25, v3
	v_min_f32_e32 v3, 0, v4
	v_mul_f32_e64 v4, |v4|, s59
	v_exp_f32_e32 v4, v4
	v_add_f32_e32 v20, 1.0, v20
	v_log_f32_e32 v20, v20
	v_add_f32_e32 v5, v84, v7
	v_add_f32_e32 v4, 1.0, v4
	v_mul_f32_e64 v6, |v5|, s59
	v_log_f32_e32 v27, v4
	v_exp_f32_e32 v6, v6
	v_pk_fma_f32 v[0:1], v[20:21], s[14:15], v[0:1] op_sel_hi:[1,0,1] neg_lo:[1,0,0] neg_hi:[1,0,0]
	v_min_f32_e32 v65, 0, v5
	v_pk_mul_f32 v[92:93], v[0:1], s[24:25] op_sel_hi:[1,0]
	v_pk_fma_f32 v[0:1], v[24:25], s[14:15], v[22:23] op_sel_hi:[1,0,1] neg_lo:[1,0,0] neg_hi:[1,0,0]
	v_add_f32_e32 v4, 1.0, v6
	v_pk_mul_f32 v[94:95], v[0:1], s[24:25] op_sel_hi:[1,0]
	v_pk_fma_f32 v[0:1], v[26:27], s[14:15], v[2:3] op_sel_hi:[1,0,1] neg_lo:[1,0,0] neg_hi:[1,0,0]
	v_add_f32_e32 v3, v84, v8
	v_min_f32_e32 v2, 0, v3
	v_mul_f32_e64 v3, |v3|, s59
	v_add_f32_e32 v5, v84, v9
	v_log_f32_e32 v67, v4
	v_exp_f32_e32 v3, v3
	v_mul_f32_e64 v4, |v5|, s59
	v_exp_f32_e32 v7, v4
	v_min_f32_e32 v6, 0, v5
	v_add_f32_e32 v3, 1.0, v3
	v_log_f32_e32 v4, v3
	v_add_f32_e32 v3, 1.0, v7
	v_log_f32_e32 v8, v3
	v_add_f32_e32 v3, v84, v10
	v_min_f32_e32 v10, 0, v3
	v_mul_f32_e64 v3, |v3|, s59
	v_add_f32_e32 v5, v84, v11
	v_exp_f32_e32 v3, v3
	v_mul_f32_e64 v7, |v5|, s59
	v_exp_f32_e32 v7, v7
	v_min_f32_e32 v22, 0, v5
	v_add_f32_e32 v3, 1.0, v3
	v_log_f32_e32 v20, v3
	v_add_f32_e32 v3, 1.0, v7
	v_add_f32_e32 v5, v84, v12
	v_log_f32_e32 v24, v3
	v_min_f32_e32 v3, 0, v5
	v_mul_f32_e64 v5, |v5|, s59
	v_add_f32_e32 v7, v84, v13
	v_exp_f32_e32 v5, v5
	v_mul_f32_e64 v9, |v7|, s59
	v_add_f32_e32 v12, v84, v14
	v_exp_f32_e32 v9, v9
	v_min_f32_e32 v11, 0, v12
	v_mul_f32_e64 v12, |v12|, s59
	v_add_f32_e32 v13, v84, v15
	v_exp_f32_e32 v12, v12
	v_mul_f32_e64 v14, |v13|, s59
	v_exp_f32_e32 v14, v14
	v_add_f32_e32 v5, 1.0, v5
	v_log_f32_e32 v5, v5
	v_add_f32_e32 v9, 1.0, v9
	v_log_f32_e32 v9, v9
	v_add_f32_e32 v12, 1.0, v12
	v_log_f32_e32 v21, v12
	v_add_f32_e32 v12, 1.0, v14
	v_log_f32_e32 v25, v12
	v_min_f32_e32 v7, 0, v7
	v_pk_fma_f32 v[2:3], v[4:5], s[14:15], v[2:3] op_sel_hi:[1,0,1] neg_lo:[1,0,0] neg_hi:[1,0,0]
	v_min_f32_e32 v23, 0, v13
	v_pk_mul_f32 v[98:99], v[2:3], s[24:25] op_sel_hi:[1,0]
	v_pk_fma_f32 v[2:3], v[8:9], s[14:15], v[6:7] op_sel_hi:[1,0,1] neg_lo:[1,0,0] neg_hi:[1,0,0]
	v_pk_mul_f32 v[96:97], v[0:1], s[24:25] op_sel_hi:[1,0]
	v_pk_mul_f32 v[100:101], v[2:3], s[24:25] op_sel_hi:[1,0]
	v_pk_fma_f32 v[2:3], v[20:21], s[14:15], v[10:11] op_sel_hi:[1,0,1] neg_lo:[1,0,0] neg_hi:[1,0,0]
	v_pk_fma_f32 v[0:1], v[66:67], s[14:15], v[64:65] op_sel_hi:[1,0,1] neg_lo:[1,0,0] neg_hi:[1,0,0]
	v_pk_mul_f32 v[102:103], v[2:3], s[24:25] op_sel_hi:[1,0]
	v_pk_fma_f32 v[2:3], v[24:25], s[14:15], v[22:23] op_sel_hi:[1,0,1] neg_lo:[1,0,0] neg_hi:[1,0,0]
	v_pk_mul_f32 v[0:1], v[0:1], s[24:25] op_sel_hi:[1,0]
	v_pk_mul_f32 v[10:11], v[2:3], s[24:25] op_sel_hi:[1,0]
	s_cbranch_scc1 .LBB0_210
	v_pk_add_f32 v[22:23], v[82:83], v[28:29]
	v_pk_add_f32 v[12:13], v[90:91], v[30:31]
	v_pk_add_f32 v[6:7], v[96:97], v[0:1]
	v_pk_add_f32 v[2:3], v[102:103], v[10:11]
	v_pk_add_f32 v[24:25], v[78:79], v[22:23]
	v_pk_add_f32 v[14:15], v[88:89], v[12:13]
	v_pk_add_f32 v[8:9], v[94:95], v[6:7]
	v_pk_add_f32 v[4:5], v[100:101], v[2:3]
	v_pk_add_f32 v[70:71], v[74:75], v[24:25]
	v_pk_add_f32 v[64:65], v[86:87], v[14:15]
	v_pk_add_f32 v[26:27], v[92:93], v[8:9]
	v_pk_add_f32 v[20:21], v[98:99], v[4:5]
	s_mov_b64 s[0:1], 0
	v_mov_b32_e32 v85, v24
	v_mov_b32_e32 v84, v70
	v_mov_b64_e32 v[66:67], v[20:21]
	v_mov_b64_e32 v[68:69], v[26:27]
	v_mov_b64_e32 v[72:73], v[64:65]
	v_mov_b64_e32 v[76:77], v[70:71]

; #define LAS __attribute__((address_space(3)))
; __device__ __forceinline__ void g1_unit(const GPre& R, bf16* __restrict__ STATE, float* __restrict__ DEC, int n, int h, LAS char* lds) {
;     ...
;   { const LAS float* Bf = (const LAS float*)(lds + L_BD); const LAS float* Bb = Bf + 64 * GS;
;     float kef[8], keb[8];
; #pragma unroll
;     for (int j = 0; j < 8; ++j) { const int d = dg * 8 + j; const float kv = (j & 1) ? bfhi(kk[j >> 1]) : bflo(kk[j >> 1]);
;       const float bl = Bf[63 * GS + d], b0 = Bb[d];
;       kef[j] = kv * __builtin_amdgcn_exp2f(bl - Bf[s * GS + d]); keb[j] = kv * __builtin_amdgcn_exp2f(b0 - Bb[s * GS + d]);
;       if (s == 0) { DEC[((size_t)(0 * NCHUNK + n) * 4 + h) * 64 + d] = __builtin_amdgcn_exp2f(bl); DEC[((size_t)(1 * NCHUNK + n) * 4 + h) * 64 + d] = __builtin_amdgcn_exp2f(b0); } }
.LBB0_217:
	s_ashr_i32 s28, s30, 2
	s_ashr_i32 s29, s28, 31
	s_and_b32 s33, s30, 3
	s_lshl_b64 s[0:1], s[28:29], 10
	s_add_u32 s0, s4, s0
	s_addc_u32 s1, s5, s1
	s_lshl_b32 s76, s33, 8
	v_and_b32_e32 v69, 7, v80
	s_add_u32 s30, s0, s76
	v_ashrrev_i32_e32 v68, 3, v80
	s_addc_u32 s31, s1, 0
	s_add_i32 s0, s28, 0x300
	v_lshl_add_u32 v2, v69, 5, 0
	s_waitcnt lgkmcnt(0)
	s_barrier
	s_ashr_i32 s1, s0, 31
	v_add_u32_e32 v66, 0x4200, v2
	s_waitcnt vmcnt(0)
	v_mad_u64_u32 v[8:9], s[50:51], v68, s58, v[2:3]
	s_lshl_b64 s[48:49], s[0:1], 10
	ds_read2_b32 v[0:1], v66 offset0:60 offset1:128
	ds_read2st64_b32 v[2:3], v8 offset1:68
	s_add_u32 s48, s4, s48
	s_addc_u32 s49, s5, s49
	v_lshlrev_b32_e32 v4, 3, v69
	s_add_u32 s48, s48, s76
	v_cmp_gt_u32_e32 vcc, 8, v80
	s_addc_u32 s49, s49, 0
	v_lshlrev_b32_e32 v70, 2, v4
	s_and_saveexec_b64 s[50:51], vcc
	s_cbranch_execz .LBB0_219
	s_waitcnt lgkmcnt(1)
	v_exp_f32_e32 v4, v0
	v_exp_f32_e32 v5, v1
	global_store_dword v70, v4, s[30:31]
	global_store_dword v70, v5, s[48:49]

; #define LAS __attribute__((address_space(3)))
; __global__ void __launch_bounds__(NWAVES * 64, 2) hymba_fwd(Args args) {
;     ...
;     { gla::GPre cur, nxt; int u = bid;
;       if (u < NCHUNK * 4) gla::load_pre<true>(cur, PROJ, args, WGT, STATE, u >> 2, u & 3);
;       for (; u < NCHUNK * 4; u += G) { const int un = u + G;
;         if (un < NCHUNK * 4) gla::load_pre<true>(nxt, PROJ, args, WGT, STATE, un >> 2, un & 3);
;         gla::g3_unit(cur, args.in[15], H, u >> 2, u & 3, (LAS char*)ldsl); cur = nxt; } }
.LBB0_406:
	s_lshl_b32 s15, s2, 4
	s_lshl_b32 s28, s74, 4
	s_lshl_b32 s29, s2, 7
	s_lshl_b32 s30, s74, 7
	s_movk_i32 s31, 0x1a00
	s_mov_b32 s7, 0
	v_mov_b32_e32 v185, 0
	s_movk_i32 s35, 0x1000
	s_mov_b64 s[8:9], 0x1000
	s_mov_b64 s[10:11], 0x3000000
	s_mov_b32 s49, 0x3000000
	s_movk_i32 s51, 0x1800
	s_movk_i32 s58, 0x110
	s_add_i32 s59, 0, 0x11000
	s_mov_b32 s64, 0xbfb8aa3b
	s_mov_b32 s14, 0x3f317218
	s_mov_b32 s48, 0x3db8aa3b
	s_movk_i32 s65, 0x44
	s_mov_b32 s50, 0x3e000000
	s_mov_b32 s80, 0xffff0000
	s_movk_i32 s81, 0x7fff
	s_movk_i32 s82, 0x90
	s_mov_b32 s83, 0x17800
	s_mov_b32 s84, 0x1c000
	s_movk_i32 s85, 0x48
	v_mov_b32_e32 v191, 0x358637bd
	s_mov_b32 s86, 0xf800000
	v_mov_b32_e32 v192, 0x260
	s_mov_b32 s87, s2
	s_waitcnt vmcnt(0)
	s_branch .LBB0_408

; __device__ __forceinline__ int crow(int r, int hi) { return (r & 3) + 8 * (r >> 2) + 4 * hi; }
; template <bool G3>
; __device__ __forceinline__ void load_pre(GPre& R, const bf16* __restrict__ P, const Args& a, const bf16* __restrict__ WGT, const bf16* __restrict__ STATE, int n, int h) {
;   int tid_ = threadIdx.x; asm volatile("" : "+v"(tid_)); const int tid = tid_, lane = tid & 63, wid = __builtin_amdgcn_readfirstlane(tid >> 6), r32 = lane & 31, hi = lane >> 5, row0 = n * 64, s = tid >> 3, dg = tid & 7;
;   R.kk = *(const v4u*)(P + (size_t)(row0 + s) * LDP + C_GK + h * 64 + dg * 8);
;   if (G3) { R.qq = *(const v4u*)(P + (size_t)(row0 + s) * LDP + C_GQ + h * 64 + dg * 8);
;     const int ct_ = wid >> 2, et_ = wid & 3;
; #pragma unroll
;     for (int r = 0; r < 16; ++r) R.grv[r] = P[(size_t)(row0 + 32 * ct_ + crow(r, hi)) * LDP + C_GR + h * 128 + 32 * et_ + r32]; }
.LBB0_408:
	s_add_i32 s87, s87, s74
	s_cmpk_gt_i32 s87, 0xbff
	s_cselect_b64 s[24:25], -1, 0
	s_and_b64 vcc, exec, s[24:25]
	s_cbranch_vccnz .LBB0_414
	v_mov_b32_e32 v233, v210
	s_ashr_i32 s0, s87, 2
	v_readfirstlane_b32 s33, v233
	s_ashr_i32 s1, s33, 3
	s_lshl_b32 s3, s0, 6
	s_andn2_b32 s1, s1, 31
	v_bfe_u32 v232, v233, 5, 1
	v_ashrrev_i32_e32 v16, 3, v233
	s_add_i32 s1, s1, s3
	v_add_u32_e32 v16, s3, v16
	v_mov_b64_e32 v[136:137], s[44:45]
	v_lshl_or_b32 v154, v232, 2, s1
	s_and_b32 s72, s87, 3
	v_mad_i64_i32 v[16:17], s[4:5], v16, s31, v[136:137]
	v_mad_i64_i32 v[138:139], s[4:5], v154, s31, v[136:137]
	s_lshl_b32 s6, s72, 7
	v_lshlrev_b32_e32 v18, 4, v233
	s_lshl_b32 s4, s72, 8
	s_mov_b32 s5, s7
	v_and_b32_e32 v231, 31, v233
	v_lshl_add_u64 v[16:17], v[16:17], 0, s[6:7]
	v_and_b32_e32 v184, 0x70, v18
	v_lshl_add_u64 v[138:139], v[138:139], 0, s[4:5]
	s_and_b32 s26, s33, 0xc0
	s_mov_b32 s27, s7
	v_or_b32_e32 v140, 1, v154
	v_lshl_add_u64 v[20:21], v[16:17], 0, v[184:185]
	v_lshl_add_u64 v[138:139], v[138:139], 0, s[26:27]
	v_lshlrev_b32_e32 v184, 1, v231
	v_mad_i64_i32 v[140:141], s[76:77], v140, s31, v[136:137]
	v_lshl_add_u64 v[138:139], v[138:139], 0, v[184:185]
	v_lshl_add_u64 v[140:141], v[140:141], 0, s[4:5]
	v_or_b32_e32 v142, 2, v154
	v_add_co_u32_e32 v138, vcc, s35, v138
	v_lshl_add_u64 v[140:141], v[140:141], 0, s[26:27]
	v_mad_i64_i32 v[142:143], s[76:77], v142, s31, v[136:137]
	v_addc_co_u32_e32 v139, vcc, 0, v139, vcc
	v_lshl_add_u64 v[140:141], v[140:141], 0, v[184:185]
	v_lshl_add_u64 v[142:143], v[142:143], 0, s[4:5]
	v_or_b32_e32 v144, 3, v154
	v_add_co_u32_e32 v140, vcc, s35, v140
	v_lshl_add_u64 v[142:143], v[142:143], 0, s[26:27]
	v_mad_i64_i32 v[144:145], s[76:77], v144, s31, v[136:137]
	v_addc_co_u32_e32 v141, vcc, 0, v141, vcc
	v_lshl_add_u64 v[142:143], v[142:143], 0, v[184:185]
	v_lshl_add_u64 v[144:145], v[144:145], 0, s[4:5]
	v_or_b32_e32 v146, 8, v154
	v_add_co_u32_e32 v142, vcc, s35, v142
	v_lshl_add_u64 v[144:145], v[144:145], 0, s[26:27]
	v_mad_i64_i32 v[146:147], s[76:77], v146, s31, v[136:137]
	v_addc_co_u32_e32 v143, vcc, 0, v143, vcc
	v_lshl_add_u64 v[144:145], v[144:145], 0, v[184:185]
	v_lshl_add_u64 v[146:147], v[146:147], 0, s[4:5]
	v_or_b32_e32 v148, 9, v154
	v_add_co_u32_e32 v144, vcc, s35, v144
	v_lshl_add_u64 v[146:147], v[146:147], 0, s[26:27]
	v_mad_i64_i32 v[148:149], s[76:77], v148, s31, v[136:137]
	v_addc_co_u32_e32 v145, vcc, 0, v145, vcc
	v_lshl_add_u64 v[146:147], v[146:147], 0, v[184:185]
	v_lshl_add_u64 v[148:149], v[148:149], 0, s[4:5]
	v_or_b32_e32 v150, 10, v154
	v_add_co_u32_e32 v146, vcc, s35, v146
	v_lshl_add_u64 v[148:149], v[148:149], 0, s[26:27]
	v_mad_i64_i32 v[150:151], s[76:77], v150, s31, v[136:137]
	v_addc_co_u32_e32 v147, vcc, 0, v147, vcc
	v_lshl_add_u64 v[148:149], v[148:149], 0, v[184:185]
	v_lshl_add_u64 v[150:151], v[150:151], 0, s[4:5]
	v_or_b32_e32 v152, 11, v154
	v_add_co_u32_e32 v148, vcc, s35, v148
	v_lshl_add_u64 v[150:151], v[150:151], 0, s[26:27]
	v_mad_i64_i32 v[152:153], s[76:77], v152, s31, v[136:137]
	v_addc_co_u32_e32 v149, vcc, 0, v149, vcc
	v_lshl_add_u64 v[150:151], v[150:151], 0, v[184:185]
	v_lshl_add_u64 v[152:153], v[152:153], 0, s[4:5]
	v_add_co_u32_e32 v150, vcc, s35, v150
	v_lshl_add_u64 v[152:153], v[152:153], 0, s[26:27]
	s_nop 0
	v_addc_co_u32_e32 v151, vcc, 0, v151, vcc
	v_lshl_add_u64 v[152:153], v[152:153], 0, v[184:185]
	v_add_co_u32_e32 v152, vcc, s35, v152
	global_load_dwordx4 v[16:19], v[20:21], off offset:3584
	s_nop 0
	global_load_dwordx4 v[20:23], v[20:21], off offset:3072
	v_addc_co_u32_e32 v153, vcc, 0, v153, vcc
	global_load_ushort v197, v[138:139], off offset:1024
	global_load_ushort v198, v[140:141], off offset:1024
	global_load_ushort v199, v[142:143], off offset:1024
	global_load_ushort v200, v[144:145], off offset:1024
	global_load_ushort v201, v[146:147], off offset:1024
	global_load_ushort v202, v[148:149], off offset:1024
	global_load_ushort v203, v[150:151], off offset:1024
	global_load_ushort v204, v[152:153], off offset:1024
	v_or_b32_e32 v138, 16, v154
	v_mad_i64_i32 v[138:139], s[76:77], v138, s31, v[136:137]
	v_lshl_add_u64 v[138:139], v[138:139], 0, s[4:5]
	v_or_b32_e32 v140, 17, v154
	v_lshl_add_u64 v[138:139], v[138:139], 0, s[26:27]
	v_mad_i64_i32 v[140:141], s[76:77], v140, s31, v[136:137]
	v_lshl_add_u64 v[138:139], v[138:139], 0, v[184:185]
	v_lshl_add_u64 v[140:141], v[140:141], 0, s[4:5]
	v_or_b32_e32 v142, 18, v154
; __device__ __forceinline__ int crow(int r, int hi) { return (r & 3) + 8 * (r >> 2) + 4 * hi; }
; template <bool G3>
; __device__ __forceinline__ void load_pre(GPre& R, const bf16* __restrict__ P, const Args& a, const bf16* __restrict__ WGT, const bf16* __restrict__ STATE, int n, int h) {
;     ...
;     for (int r = 0; r < 16; ++r) R.grv[r] = P[(size_t)(row0 + 32 * ct_ + crow(r, hi)) * LDP + C_GR + h * 128 + 32 * et_ + r32]; }
;   if (wid < 4) { const int dir = wid >> 1, dt = wid & 1, c = h * 64 + 32 * dt + r32;
;     R.wb = *(const bf16x8*)(WGT + ((size_t)dir * 256 + c) * 16 + 8 * hi); R.bias = (dir ? a.in[14] : a.in[12])[c];
;     R.lr0 = *(const bf16x8*)(P + (size_t)(row0 + r32) * LDP + (dir ? C_LRB : C_LRF) + 8 * hi); R.lr1 = *(const bf16x8*)(P + (size_t)(row0 + 32 + r32) * LDP + (dir ? C_LRB : C_LRF) + 8 * hi);
;   } else { const int t = tid - 256, s2 = t >> 2, part = t & 3;
;     { const v4u* src = (const v4u*)(P + (size_t)(row0 + s2) * LDP + C_GV + h * 128 + part * 32); R.vv[0] = src[0]; R.vv[1] = src[1]; R.vv[2] = src[2]; R.vv[3] = src[3]; }
;     if (G3) { const v4u* sf = (const v4u*)(STATE + ((size_t)(0 * NCHUNK + n) * 4 + h) * 8192 + s2 * 128 + part * 32); const v4u* sb = (const v4u*)(STATE + ((size_t)(1 * NCHUNK + n) * 4 + h) * 8192 + s2 * 128 + part * 32);
; #pragma unroll
;       for (int i = 0; i < 4; ++i) { R.sfv[i] = sf[i]; R.sbv[i] = sb[i]; } }
	v_add_co_u32_e32 v138, vcc, s35, v138
	v_lshl_add_u64 v[140:141], v[140:141], 0, s[26:27]
	v_mad_i64_i32 v[142:143], s[76:77], v142, s31, v[136:137]
	v_addc_co_u32_e32 v139, vcc, 0, v139, vcc
	v_lshl_add_u64 v[140:141], v[140:141], 0, v[184:185]
	v_lshl_add_u64 v[142:143], v[142:143], 0, s[4:5]
	v_or_b32_e32 v144, 19, v154
	v_add_co_u32_e32 v140, vcc, s35, v140
	v_lshl_add_u64 v[142:143], v[142:143], 0, s[26:27]
	v_mad_i64_i32 v[144:145], s[76:77], v144, s31, v[136:137]
	v_addc_co_u32_e32 v141, vcc, 0, v141, vcc
	v_lshl_add_u64 v[142:143], v[142:143], 0, v[184:185]
	v_lshl_add_u64 v[144:145], v[144:145], 0, s[4:5]
	v_or_b32_e32 v146, 24, v154
	v_add_co_u32_e32 v142, vcc, s35, v142
	v_lshl_add_u64 v[144:145], v[144:145], 0, s[26:27]
	v_mad_i64_i32 v[146:147], s[76:77], v146, s31, v[136:137]
	v_addc_co_u32_e32 v143, vcc, 0, v143, vcc
	v_lshl_add_u64 v[144:145], v[144:145], 0, v[184:185]
	v_lshl_add_u64 v[146:147], v[146:147], 0, s[4:5]
	v_or_b32_e32 v148, 25, v154
	v_add_co_u32_e32 v144, vcc, s35, v144
	v_lshl_add_u64 v[146:147], v[146:147], 0, s[26:27]
	v_mad_i64_i32 v[148:149], s[76:77], v148, s31, v[136:137]
	v_addc_co_u32_e32 v145, vcc, 0, v145, vcc
	v_lshl_add_u64 v[146:147], v[146:147], 0, v[184:185]
	v_lshl_add_u64 v[148:149], v[148:149], 0, s[4:5]
	v_or_b32_e32 v150, 26, v154
	v_add_co_u32_e32 v146, vcc, s35, v146
	v_lshl_add_u64 v[148:149], v[148:149], 0, s[26:27]
	v_mad_i64_i32 v[150:151], s[76:77], v150, s31, v[136:137]
	v_addc_co_u32_e32 v147, vcc, 0, v147, vcc
	v_lshl_add_u64 v[148:149], v[148:149], 0, v[184:185]
	v_lshl_add_u64 v[150:151], v[150:151], 0, s[4:5]
	v_or_b32_e32 v152, 27, v154
	v_add_co_u32_e32 v148, vcc, s35, v148
	v_lshl_add_u64 v[150:151], v[150:151], 0, s[26:27]
	v_mad_i64_i32 v[136:137], s[76:77], v152, s31, v[136:137]
	v_addc_co_u32_e32 v149, vcc, 0, v149, vcc
	v_lshl_add_u64 v[150:151], v[150:151], 0, v[184:185]
	v_lshl_add_u64 v[136:137], v[136:137], 0, s[4:5]
	v_add_co_u32_e32 v150, vcc, s35, v150
	v_lshl_add_u64 v[136:137], v[136:137], 0, s[26:27]
	s_nop 0
	v_addc_co_u32_e32 v151, vcc, 0, v151, vcc
	v_lshl_add_u64 v[136:137], v[136:137], 0, v[184:185]
	v_add_co_u32_e32 v136, vcc, 0x1000, v136
	s_ashr_i32 s26, s33, 6
	s_nop 0
	v_addc_co_u32_e32 v137, vcc, 0, v137, vcc
	global_load_ushort v205, v[138:139], off offset:1024
	global_load_ushort v206, v[140:141], off offset:1024
	global_load_ushort v207, v[142:143], off offset:1024
	global_load_ushort v208, v[144:145], off offset:1024
	global_load_ushort v209, v[146:147], off offset:1024
	global_load_ushort v219, v[148:149], off offset:1024
	global_load_ushort v220, v[150:151], off offset:1024
	global_load_ushort v221, v[136:137], off offset:1024
	s_cmp_gt_i32 s26, 3
	s_mov_b64 s[4:5], -1
	s_cbranch_scc0 .LBB0_411
	v_add_u32_e32 v136, 0xffffff00, v233
	v_ashrrev_i32_e32 v152, 2, v136
	s_ashr_i32 s1, s0, 31
	v_add_u32_e32 v138, s3, v152
	v_mov_b64_e32 v[136:137], s[44:45]
	s_lshl_b32 s6, s6, 1
	s_lshl_b64 s[0:1], s[0:1], 16
	v_mad_i64_i32 v[136:137], s[4:5], v138, s31, v[136:137]
	s_add_u32 s0, s68, s0
	v_lshlrev_b32_e32 v138, 6, v233
	s_addc_u32 s1, s69, s1
	s_lshl_b32 s4, s72, 14
	v_lshl_add_u64 v[136:137], v[136:137], 0, s[6:7]
	v_and_b32_e32 v184, 0xc0, v138
	s_add_u32 s0, s0, s4
	v_lshlrev_b32_e32 v152, 7, v152
	v_lshl_add_u64 v[136:137], v[136:137], 0, v[184:185]
	s_addc_u32 s1, s1, 0
	v_ashrrev_i32_e32 v153, 31, v152
	v_lshl_add_u64 v[140:141], v[136:137], 0, s[8:9]
	v_add_co_u32_e32 v136, vcc, 0x1000, v136
	v_lshl_add_u64 v[152:153], v[152:153], 1, s[0:1]
	s_nop 0
	v_addc_co_u32_e32 v137, vcc, 0, v137, vcc
	v_lshl_add_u64 v[168:169], v[152:153], 0, v[184:185]
	global_load_dwordx4 v[80:83], v[136:137], off
	s_nop 0
	global_load_dwordx4 v[68:71], v[140:141], off offset:48
	global_load_dwordx4 v[72:75], v[140:141], off offset:32
	s_nop 0
	global_load_dwordx4 v[76:79], v[140:141], off offset:16
	v_lshl_add_u64 v[172:173], v[168:169], 0, s[10:11]
	global_load_dwordx4 v[48:51], v[168:169], off offset:48
	global_load_dwordx4 v[56:59], v[168:169], off offset:32
	global_load_dwordx4 v[60:63], v[168:169], off offset:16
	global_load_dwordx4 v[64:67], v[168:169], off
	v_add_co_u32_e32 v168, vcc, s49, v168
	s_mov_b64 s[4:5], 0
	s_nop 0
	v_addc_co_u32_e32 v169, vcc, 0, v169, vcc
	global_load_dwordx4 v[44:47], v[168:169], off
	s_nop 0
	global_load_dwordx4 v[28:31], v[172:173], off offset:48
	global_load_dwordx4 v[32:35], v[172:173], off offset:32
	s_nop 0
	global_load_dwordx4 v[36:39], v[172:173], off offset:16

; #define LAS __attribute__((address_space(3)))
; template <bool WITH_S>
; __device__ __forceinline__ void prep(const GPre& R, int n, int h, LAS char* lds) {
;     ...
;   if (wid < 4) {
;     const int dir = wid >> 1, dt = wid & 1;
;     const bf16x8 bfr = R.wb;
;     const float bias = R.bias;
;     float g[32];
; #pragma unroll
;     for (int st = 0; st < 2; ++st) { const bf16x8 afr = st ? R.lr1 : R.lr0;
;       f32x16 z = {}; z = __builtin_amdgcn_mfma_f32_32x32x16_bf16(afr, bfr, z, 0, 0, 0);
; #pragma unroll
;       for (int r = 0; r < 16; ++r) g[16 * st + r] = logsig(z[r] + bias) * (0.0625f * 1.4426950408889634f); }
;     float T[8], Tp[8];
;     if (dir == 0) {
; #pragma unroll
;       for (int i = 0; i < 8; ++i) { g[4 * i + 1] += g[4 * i]; g[4 * i + 2] += g[4 * i + 1]; g[4 * i + 3] += g[4 * i + 2]; T[i] = g[4 * i + 3]; }
;     } else {
; #pragma unroll
;       for (int i = 0; i < 8; ++i) { g[4 * i + 2] += g[4 * i + 3]; g[4 * i + 1] += g[4 * i + 2]; g[4 * i] += g[4 * i + 1]; T[i] = g[4 * i]; }
;     }
; #pragma unroll
;     for (int i = 0; i < 8; ++i) Tp[i] = __shfl_xor(T[i], 32);
;     if (dir == 0) { float run = 0.f;
; #pragma unroll
;       for (int i = 0; i < 8; ++i) { const float E = run + (hi ? Tp[i] : 0.f); run += T[i] + Tp[i];
; #pragma unroll
;         for (int q = 0; q < 4; ++q) g[4 * i + q] += E; }
;     } else { float run = 0.f;
; #pragma unroll
;       for (int i = 7; i >= 0; --i) { const float E = run + (hi ? 0.f : Tp[i]); run += T[i] + Tp[i];
; #pragma unroll
;         for (int q = 0; q < 4; ++q) g[4 * i + q] += E; }
;     }
;     LAS float* B = (LAS float*)(lds + L_BD) + dir * 64 * GS + 32 * dt + r32;
; #pragma unroll
;     for (int i = 0; i < 8; ++i)
; #pragma unroll
;       for (int q = 0; q < 4; ++q) { const int s = 32 * (i >> 2) + q + 8 * (i & 3) + 4 * hi; B[s * GS] = g[4 * i + q]; }
;   } else {
;     const int t = tid - 256, s = t >> 2, part = t & 3;
;     { LAS v4u* dst = (LAS v4u*)(lds + L_V + s * VS + part * 64); dst[0] = R.vv[0]; dst[1] = R.vv[1]; dst[2] = R.vv[2]; dst[3] = R.vv[3]; }
;     if (WITH_S) { LAS v4u* df = (LAS v4u*)(lds + L_SF + s * VS + part * 64); LAS v4u* db = (LAS v4u*)(lds + L_SB + s * VS + part * 64);
; #pragma unroll
;       for (int i = 0; i < 4; ++i) { df[i] = R.sfv[i]; db[i] = R.sbv[i]; } }
.LBB0_413:
.LBB0_414:
	v_mov_b32_e32 v162, v210
	v_mov_b32_e32 v163, v210
	s_mov_b64 s[0:1], -1
	v_readfirstlane_b32 s26, v163
	s_ashr_i32 s6, s26, 6
	v_readfirstlane_b32 s3, v162
	s_cmp_gt_i32 s6, 3
	s_cbranch_scc0 .LBB0_416
	v_add_u32_e32 v136, 0xffffff00, v163
	v_lshrrev_b32_e32 v136, 2, v136
	v_lshlrev_b32_e32 v137, 6, v163
	v_mul_lo_u32 v136, v136, s58
	v_and_b32_e32 v137, 0xc0, v137
	v_add3_u32 v138, 0, v136, v137
	ds_write_b128 v138, v[8:11] offset:34816
	ds_write_b128 v138, v[12:15] offset:34832
	ds_write_b128 v138, v[4:7] offset:34848
	ds_write_b128 v138, v[0:3] offset:34864
	v_add3_u32 v0, s59, v136, v137
	ds_write_b128 v138, v[112:115] offset:52224
	ds_write_b128 v0, v[128:131]
	ds_write_b128 v138, v[108:111] offset:52240
	ds_write_b128 v0, v[124:127] offset:16
	ds_write_b128 v138, v[104:107] offset:52256
	ds_write_b128 v0, v[120:123] offset:32
	ds_write_b128 v138, v[100:103] offset:52272
	ds_write_b128 v0, v[116:119] offset:48
	s_mov_b64 s[0:1], 0
.LBB0_416:
	s_andn2_b64 vcc, exec, s[0:1]
	s_cbranch_vccnz .LBB0_426
	v_mfma_f32_32x32x16_bf16 v[0:15], v[132:135], v[92:95], 0
	s_cmpk_gt_u32 s26, 0x7f
	s_cselect_b64 s[4:5], -1, 0
	s_cmpk_lt_u32 s26, 0x80
	s_mov_b64 s[0:1], -1
	s_nop 7
	v_add_f32_e32 v1, v230, v1
	v_add_f32_e32 v101, v230, v2
	v_min_f32_e32 v2, 0, v1
	v_mul_f32_e64 v1, |v1|, s64
	v_exp_f32_e32 v1, v1
	v_add_f32_e32 v100, v230, v0
	v_min_f32_e32 v0, 0, v100
	v_mul_f32_e64 v100, |v100|, s64
	v_exp_f32_e32 v102, v100
	v_min_f32_e32 v100, 0, v101
	v_mul_f32_e64 v101, |v101|, s64
	v_add_f32_e32 v1, 1.0, v1
	v_add_f32_e32 v3, v230, v3
	v_log_f32_e32 v104, v1
	v_exp_f32_e32 v1, v101
	v_mul_f32_e64 v101, |v3|, s64
	v_exp_f32_e32 v101, v101
	v_min_f32_e32 v108, 0, v3
	v_add_f32_e32 v1, 1.0, v1
	v_log_f32_e32 v106, v1
	v_add_f32_e32 v1, 1.0, v101
	v_add_f32_e32 v3, v230, v4
	v_log_f32_e32 v110, v1
	v_min_f32_e32 v1, 0, v3
	v_mul_f32_e64 v3, |v3|, s64
	v_add_f32_e32 v4, v230, v5
	v_exp_f32_e32 v3, v3
	v_mul_f32_e64 v5, |v4|, s64
	v_exp_f32_e32 v5, v5
	v_add_f32_e32 v102, 1.0, v102
	v_add_f32_e32 v3, 1.0, v3
	v_log_f32_e32 v103, v3
	v_min_f32_e32 v3, 0, v4
	v_add_f32_e32 v4, 1.0, v5
	v_log_f32_e32 v105, v4
	v_add_f32_e32 v4, v230, v6
	v_min_f32_e32 v101, 0, v4
	v_mul_f32_e64 v4, |v4|, s64
	v_add_f32_e32 v5, v230, v7
	v_exp_f32_e32 v4, v4
	v_mul_f32_e64 v6, |v5|, s64
	v_exp_f32_e32 v6, v6
	v_log_f32_e32 v102, v102
	v_add_f32_e32 v4, 1.0, v4
	v_log_f32_e32 v107, v4
	v_add_f32_e32 v4, 1.0, v6
	v_log_f32_e32 v111, v4
	v_pk_fma_f32 v[0:1], v[102:103], s[14:15], v[0:1] op_sel_hi:[1,0,1] neg_lo:[1,0,0] neg_hi:[1,0,0]
	v_min_f32_e32 v109, 0, v5
	v_pk_mul_f32 v[112:113], v[0:1], s[48:49] op_sel_hi:[1,0]
	v_pk_fma_f32 v[0:1], v[104:105], s[14:15], v[2:3] op_sel_hi:[1,0,1] neg_lo:[1,0,0] neg_hi:[1,0,0]
	v_add_f32_e32 v3, v230, v9
	v_pk_mul_f32 v[118:119], v[0:1], s[48:49] op_sel_hi:[1,0]
	v_pk_fma_f32 v[0:1], v[106:107], s[14:15], v[100:101] op_sel_hi:[1,0,1] neg_lo:[1,0,0] neg_hi:[1,0,0]
	v_mul_f32_e64 v2, |v3|, s64
	v_pk_mul_f32 v[120:121], v[0:1], s[48:49] op_sel_hi:[1,0]
	v_pk_fma_f32 v[0:1], v[110:111], s[14:15], v[108:109] op_sel_hi:[1,0,1] neg_lo:[1,0,0] neg_hi:[1,0,0]
	v_exp_f32_e32 v5, v2
	v_pk_mul_f32 v[100:101], v[0:1], s[48:49] op_sel_hi:[1,0]
	v_add_f32_e32 v1, v230, v8
	v_min_f32_e32 v0, 0, v1
	v_mul_f32_e64 v1, |v1|, s64
	v_exp_f32_e32 v1, v1
	v_min_f32_e32 v4, 0, v3
	v_add_f32_e32 v3, v230, v11
	v_min_f32_e32 v102, 0, v3
	v_add_f32_e32 v1, 1.0, v1
	v_log_f32_e32 v2, v1
	v_add_f32_e32 v1, 1.0, v5
	v_log_f32_e32 v6, v1
	v_add_f32_e32 v1, v230, v10
	v_min_f32_e32 v8, 0, v1
	v_mul_f32_e64 v1, |v1|, s64
	v_exp_f32_e32 v1, v1
	v_mul_f32_e64 v5, |v3|, s64
	v_exp_f32_e32 v5, v5
	v_add_f32_e32 v3, v230, v12
	v_add_f32_e32 v1, 1.0, v1
	v_log_f32_e32 v10, v1
	v_add_f32_e32 v1, 1.0, v5
	v_log_f32_e32 v104, v1
	v_min_f32_e32 v1, 0, v3
	v_mul_f32_e64 v3, |v3|, s64
	v_add_f32_e32 v5, v230, v13
	v_exp_f32_e32 v3, v3
	v_mul_f32_e64 v7, |v5|, s64
	v_add_f32_e32 v11, v230, v14
	v_exp_f32_e32 v7, v7
	v_min_f32_e32 v9, 0, v11
	v_mul_f32_e64 v11, |v11|, s64
	v_add_f32_e32 v12, v230, v15
	v_exp_f32_e32 v11, v11
	v_mul_f32_e64 v13, |v12|, s64
	v_exp_f32_e32 v13, v13
	v_add_f32_e32 v3, 1.0, v3
	v_log_f32_e32 v3, v3
	v_add_f32_e32 v7, 1.0, v7
	v_log_f32_e32 v7, v7
	v_add_f32_e32 v11, 1.0, v11
	v_log_f32_e32 v11, v11
	v_min_f32_e32 v103, 0, v12
	v_add_f32_e32 v12, 1.0, v13
	v_log_f32_e32 v105, v12
	v_min_f32_e32 v5, 0, v5
	v_pk_fma_f32 v[0:1], v[2:3], s[14:15], v[0:1] op_sel_hi:[1,0,1] neg_lo:[1,0,0] neg_hi:[1,0,0]
	v_pk_mul_f32 v[124:125], v[0:1], s[48:49] op_sel_hi:[1,0]
	v_pk_fma_f32 v[0:1], v[6:7], s[14:15], v[4:5] op_sel_hi:[1,0,1] neg_lo:[1,0,0] neg_hi:[1,0,0]
	s_nop 0
	v_pk_mul_f32 v[126:127], v[0:1], s[48:49] op_sel_hi:[1,0]
	v_pk_fma_f32 v[0:1], v[10:11], s[14:15], v[8:9] op_sel_hi:[1,0,1] neg_lo:[1,0,0] neg_hi:[1,0,0]
	s_nop 0
; __device__ __forceinline__ float logsig(float z) { return fminf(z, 0.f) - 0.6931471805599453f * __builtin_amdgcn_logf(1.0f + __builtin_amdgcn_exp2f(-1.4426950408889634f * __builtin_fabsf(z))); }
; template <bool WITH_S>
; __device__ __forceinline__ void prep(const GPre& R, int n, int h, LAS char* lds) {
;     ...
;     for (int st = 0; st < 2; ++st) { const bf16x8 afr = st ? R.lr1 : R.lr0;
;       f32x16 z = {}; z = __builtin_amdgcn_mfma_f32_32x32x16_bf16(afr, bfr, z, 0, 0, 0);
; #pragma unroll
;       for (int r = 0; r < 16; ++r) g[16 * st + r] = logsig(z[r] + bias) * (0.0625f * 1.4426950408889634f); }
;     float T[8], Tp[8];
;     if (dir == 0) {
; #pragma unroll
;       for (int i = 0; i < 8; ++i) { g[4 * i + 1] += g[4 * i]; g[4 * i + 2] += g[4 * i + 1]; g[4 * i + 3] += g[4 * i + 2]; T[i] = g[4 * i + 3]; }
;     } else {
; #pragma unroll
;       for (int i = 0; i < 8; ++i) { g[4 * i + 2] += g[4 * i + 3]; g[4 * i + 1] += g[4 * i + 2]; g[4 * i] += g[4 * i + 1]; T[i] = g[4 * i]; }
;     }
	v_pk_mul_f32 v[128:129], v[0:1], s[48:49] op_sel_hi:[1,0]
	v_pk_fma_f32 v[0:1], v[104:105], s[14:15], v[102:103] op_sel_hi:[1,0,1] neg_lo:[1,0,0] neg_hi:[1,0,0]
	s_nop 0
	v_pk_mul_f32 v[102:103], v[0:1], s[48:49] op_sel_hi:[1,0]
	v_mfma_f32_32x32x16_bf16 v[0:15], v[96:99], v[92:95], 0
	s_nop 11
	v_add_f32_e32 v1, v230, v1
	v_mul_f32_e64 v93, |v1|, s64
	v_exp_f32_e32 v93, v93
	v_min_f32_e32 v94, 0, v1
	v_add_f32_e32 v3, v230, v3
	v_min_f32_e32 v104, 0, v3
	v_add_f32_e32 v1, 1.0, v93
	v_log_f32_e32 v96, v1
	v_add_f32_e32 v1, v230, v2
	v_min_f32_e32 v2, 0, v1
	v_mul_f32_e64 v1, |v1|, s64
	v_exp_f32_e32 v1, v1
	v_mul_f32_e64 v93, |v3|, s64
	v_exp_f32_e32 v93, v93
	v_add_f32_e32 v3, v230, v4
	v_add_f32_e32 v1, 1.0, v1
	v_log_f32_e32 v98, v1
	v_add_f32_e32 v1, 1.0, v93
	v_log_f32_e32 v106, v1
	v_min_f32_e32 v1, 0, v3
	v_mul_f32_e64 v3, |v3|, s64
	v_add_f32_e32 v4, v230, v5
	v_exp_f32_e32 v3, v3
	v_mul_f32_e64 v5, |v4|, s64
	v_exp_f32_e32 v5, v5
	v_add_f32_e32 v92, v230, v0
	v_min_f32_e32 v0, 0, v92
	v_mul_f32_e64 v92, |v92|, s64
	v_add_f32_e32 v3, 1.0, v3
	v_exp_f32_e32 v92, v92
	v_log_f32_e32 v93, v3
	v_min_f32_e32 v95, 0, v4
	v_add_f32_e32 v3, 1.0, v5
	v_add_f32_e32 v4, v230, v6
	v_log_f32_e32 v97, v3
	v_min_f32_e32 v3, 0, v4
	v_mul_f32_e64 v4, |v4|, s64
	v_exp_f32_e32 v4, v4
	v_add_f32_e32 v92, 1.0, v92
	v_log_f32_e32 v92, v92
	v_add_f32_e32 v5, v230, v7
	v_add_f32_e32 v4, 1.0, v4
	v_mul_f32_e64 v6, |v5|, s64
	v_log_f32_e32 v99, v4
	v_exp_f32_e32 v6, v6
	v_pk_fma_f32 v[0:1], v[92:93], s[14:15], v[0:1] op_sel_hi:[1,0,1] neg_lo:[1,0,0] neg_hi:[1,0,0]
	v_min_f32_e32 v105, 0, v5
	v_pk_mul_f32 v[130:131], v[0:1], s[48:49] op_sel_hi:[1,0]
	v_pk_fma_f32 v[0:1], v[96:97], s[14:15], v[94:95] op_sel_hi:[1,0,1] neg_lo:[1,0,0] neg_hi:[1,0,0]
	v_add_f32_e32 v4, 1.0, v6
	v_pk_mul_f32 v[132:133], v[0:1], s[48:49] op_sel_hi:[1,0]
	v_pk_fma_f32 v[0:1], v[98:99], s[14:15], v[2:3] op_sel_hi:[1,0,1] neg_lo:[1,0,0] neg_hi:[1,0,0]
	v_add_f32_e32 v3, v230, v8
	v_min_f32_e32 v2, 0, v3
	v_mul_f32_e64 v3, |v3|, s64
	v_add_f32_e32 v5, v230, v9
	v_log_f32_e32 v107, v4
	v_exp_f32_e32 v3, v3
	v_mul_f32_e64 v4, |v5|, s64
	v_exp_f32_e32 v7, v4
	v_min_f32_e32 v6, 0, v5
	v_add_f32_e32 v3, 1.0, v3
	v_log_f32_e32 v4, v3
	v_add_f32_e32 v3, 1.0, v7
	v_log_f32_e32 v8, v3
	v_add_f32_e32 v3, v230, v10
	v_min_f32_e32 v10, 0, v3
	v_mul_f32_e64 v3, |v3|, s64
	v_add_f32_e32 v5, v230, v11
	v_exp_f32_e32 v3, v3
	v_mul_f32_e64 v7, |v5|, s64
	v_exp_f32_e32 v7, v7
	v_min_f32_e32 v94, 0, v5
	v_add_f32_e32 v3, 1.0, v3
	v_log_f32_e32 v92, v3
	v_add_f32_e32 v3, 1.0, v7
	v_add_f32_e32 v5, v230, v12
	v_log_f32_e32 v96, v3
	v_min_f32_e32 v3, 0, v5
	v_mul_f32_e64 v5, |v5|, s64
	v_add_f32_e32 v7, v230, v13
	v_exp_f32_e32 v5, v5
	v_mul_f32_e64 v9, |v7|, s64
	v_add_f32_e32 v12, v230, v14
	v_exp_f32_e32 v9, v9
	v_min_f32_e32 v11, 0, v12
	v_mul_f32_e64 v12, |v12|, s64
	v_add_f32_e32 v13, v230, v15
	v_exp_f32_e32 v12, v12
	v_mul_f32_e64 v14, |v13|, s64
	v_exp_f32_e32 v14, v14
	v_add_f32_e32 v5, 1.0, v5
	v_log_f32_e32 v5, v5
	v_add_f32_e32 v9, 1.0, v9
	v_log_f32_e32 v9, v9
	v_add_f32_e32 v12, 1.0, v12
	v_log_f32_e32 v93, v12
	v_add_f32_e32 v12, 1.0, v14
	v_log_f32_e32 v97, v12
	v_min_f32_e32 v7, 0, v7
	v_pk_fma_f32 v[2:3], v[4:5], s[14:15], v[2:3] op_sel_hi:[1,0,1] neg_lo:[1,0,0] neg_hi:[1,0,0]
	v_min_f32_e32 v95, 0, v13
	v_pk_mul_f32 v[136:137], v[2:3], s[48:49] op_sel_hi:[1,0]
	v_pk_fma_f32 v[2:3], v[8:9], s[14:15], v[6:7] op_sel_hi:[1,0,1] neg_lo:[1,0,0] neg_hi:[1,0,0]
	v_pk_mul_f32 v[134:135], v[0:1], s[48:49] op_sel_hi:[1,0]
	v_pk_mul_f32 v[138:139], v[2:3], s[48:49] op_sel_hi:[1,0]
	v_pk_fma_f32 v[2:3], v[92:93], s[14:15], v[10:11] op_sel_hi:[1,0,1] neg_lo:[1,0,0] neg_hi:[1,0,0]
	v_pk_fma_f32 v[0:1], v[106:107], s[14:15], v[104:105] op_sel_hi:[1,0,1] neg_lo:[1,0,0] neg_hi:[1,0,0]
	v_pk_mul_f32 v[140:141], v[2:3], s[48:49] op_sel_hi:[1,0]
	v_pk_fma_f32 v[2:3], v[96:97], s[14:15], v[94:95] op_sel_hi:[1,0,1] neg_lo:[1,0,0] neg_hi:[1,0,0]
	v_pk_mul_f32 v[0:1], v[0:1], s[48:49] op_sel_hi:[1,0]
	v_pk_mul_f32 v[10:11], v[2:3], s[48:49] op_sel_hi:[1,0]
	s_cbranch_scc1 .LBB0_419
	v_pk_add_f32 v[94:95], v[120:121], v[100:101]
	v_pk_add_f32 v[12:13], v[128:129], v[102:103]
	v_pk_add_f32 v[6:7], v[134:135], v[0:1]
	v_pk_add_f32 v[2:3], v[140:141], v[10:11]
	v_pk_add_f32 v[96:97], v[118:119], v[94:95]
	v_pk_add_f32 v[14:15], v[126:127], v[12:13]
	v_pk_add_f32 v[8:9], v[132:133], v[6:7]
	v_pk_add_f32 v[4:5], v[138:139], v[2:3]
	v_pk_add_f32 v[110:111], v[112:113], v[96:97]
	v_pk_add_f32 v[104:105], v[124:125], v[14:15]
	v_pk_add_f32 v[98:99], v[130:131], v[8:9]
	v_pk_add_f32 v[92:93], v[136:137], v[4:5]
	s_mov_b64 s[0:1], 0
	v_mov_b32_e32 v123, v96
	v_mov_b32_e32 v122, v110
	v_mov_b64_e32 v[106:107], v[92:93]
	v_mov_b64_e32 v[108:109], v[98:99]
	v_mov_b64_e32 v[114:115], v[104:105]
	v_mov_b64_e32 v[116:117], v[110:111]

; #define LAS __attribute__((address_space(3)))
; __device__ __forceinline__ unsigned pk2(float lo, float hi) { return f2bf(lo) | (f2bf(hi) << 16); }
; #define LBAR() do { asm volatile("s_waitcnt lgkmcnt(0)" ::: "memory"); __builtin_amdgcn_s_barrier(); asm volatile("" ::: "memory"); } while (0)
; __device__ __forceinline__ void g3_unit(const GPre& R, const float* __restrict__ gng, bf16* __restrict__ MIXIN, int n, int h, LAS char* lds) {
;     ...
;   { const LAS float* Bf = (const LAS float*)(lds + L_BD); const LAS float* Bb = Bf + 64 * GS;
;     float qf[8], kf[8], qb[8], kb[8];
; #pragma unroll
;     for (int j = 0; j < 8; ++j) { const int d = dg * 8 + j; const float kv = (j & 1) ? bfhi(kk[j >> 1]) : bflo(kk[j >> 1]); const float qv = ((j & 1) ? bfhi(qq[j >> 1]) : bflo(qq[j >> 1])) * 0.125f;
;       const float bf_ = Bf[s * GS + d], bb_ = Bb[s * GS + d];
;       qf[j] = qv * __builtin_amdgcn_exp2f(bf_); kf[j] = kv * __builtin_amdgcn_exp2f(-bf_); qb[j] = qv * __builtin_amdgcn_exp2f(bb_); kb[j] = kv * __builtin_amdgcn_exp2f(-bb_); }
;     v4u w;
;     w.x = pk2(qf[0], qf[1]); w.y = pk2(qf[2], qf[3]); w.z = pk2(qf[4], qf[5]); w.w = pk2(qf[6], qf[7]); *(LAS v4u*)(lds + L_QTF + (s * ST72 + dg * 8) * 2) = w;
;     w.x = pk2(qb[0], qb[1]); w.y = pk2(qb[2], qb[3]); w.z = pk2(qb[4], qb[5]); w.w = pk2(qb[6], qb[7]); *(LAS v4u*)(lds + L_QTB + (s * ST72 + dg * 8) * 2) = w;
;     w.x = pk2(kf[0], kf[1]); w.y = pk2(kf[2], kf[3]); w.z = pk2(kf[4], kf[5]); w.w = pk2(kf[6], kf[7]); *(LAS v4u*)(lds + L_KTF + (s * ST72 + dg * 8) * 2) = w;
;     w.x = pk2(kb[0], kb[1]); w.y = pk2(kb[2], kb[3]); w.z = pk2(kb[4], kb[5]); w.w = pk2(kb[6], kb[7]); *(LAS v4u*)(lds + L_KTB + (s * ST72 + dg * 8) * 2) = w; }
;   LBAR();
;   { const int dir = wid >> 2, ct = (wid >> 1) & 1, st = wid & 1; f32x16 acc = {};
;     lcp Q = lds + (dir ? L_QTB : L_QTF); lcp K = lds + (dir ? L_KTB : L_KTF);
; #pragma unroll
;     for (int ks = 0; ks < 4; ++ks) acc = __builtin_amdgcn_mfma_f32_32x32x16_bf16(frag(Q, 32 * ct, 16 * ks, lane), frag(K, 32 * st, 16 * ks, lane), acc, 0, 0, 0);
.LBB0_426:
	v_ashrrev_i32_e32 v112, 3, v162
	v_and_b32_e32 v113, 7, v162
	v_mul_lo_u32 v0, v112, s65
	v_lshl_add_u32 v0, v113, 3, v0
	s_waitcnt lgkmcnt(0)
	s_barrier
	v_lshl_add_u32 v12, v0, 2, 0
	ds_read_b128 v[0:3], v12
	ds_read_b128 v[4:7], v12 offset:17408
	ds_read_b128 v[8:11], v12 offset:16
	ds_read_b128 v[12:15], v12 offset:17424
	s_add_i32 s26, 0, 0x15400
	s_add_i32 s27, 0, 0x17800
	s_waitcnt lgkmcnt(3)
	v_exp_f32_e32 v92, v0
	v_exp_f32_e32 v93, v2
	v_exp_f32_e64 v94, -v0
	v_exp_f32_e32 v0, v1
	s_waitcnt vmcnt(0)
	v_exp_f32_e64 v98, -v1
	v_exp_f32_e32 v1, v3
	v_exp_f32_e64 v99, -v3
	s_waitcnt lgkmcnt(2)
	v_exp_f32_e32 v101, v7
	v_exp_f32_e64 v103, -v7
	s_waitcnt lgkmcnt(1)
	v_exp_f32_e32 v104, v9
	v_exp_f32_e32 v3, v10
	v_exp_f32_e64 v7, -v10
	v_exp_f32_e32 v105, v11
	v_exp_f32_e64 v107, -v11
	v_lshlrev_b32_e32 v11, 16, v89
	v_lshlrev_b32_e32 v10, 16, v88
	v_pk_mul_f32 v[10:11], v[10:11], s[50:51] op_sel_hi:[1,0]
	v_exp_f32_e64 v106, -v9
	s_waitcnt lgkmcnt(0)
	v_exp_f32_e32 v108, v13
	v_exp_f32_e64 v110, -v13
	v_exp_f32_e32 v9, v14
	v_exp_f32_e64 v13, -v14
	v_exp_f32_e32 v109, v15
	v_exp_f32_e64 v111, -v15
	v_and_b32_e32 v15, 0xffff0000, v89
	v_and_b32_e32 v14, 0xffff0000, v88
	v_pk_mul_f32 v[88:89], v[10:11], v[92:93]
	v_lshlrev_b32_e32 v93, 16, v91
	v_lshlrev_b32_e32 v92, 16, v90
	v_and_b32_e32 v91, 0xffff0000, v91
	v_and_b32_e32 v90, 0xffff0000, v90
	v_exp_f32_e64 v95, -v2
	v_exp_f32_e32 v2, v8
	v_pk_mul_f32 v[90:91], v[90:91], s[50:51] op_sel_hi:[1,0]
	v_pk_mul_f32 v[14:15], v[14:15], s[50:51] op_sel_hi:[1,0]
	v_pk_mul_f32 v[104:105], v[90:91], v[104:105]
	v_pk_mul_f32 v[0:1], v[14:15], v[0:1]
	v_bfe_u32 v114, v105, 16, 1
	v_pk_mul_f32 v[92:93], v[92:93], s[50:51] op_sel_hi:[1,0]
	v_add3_u32 v105, v105, v114, s81
	v_bfe_u32 v114, v88, 16, 1
	v_pk_mul_f32 v[2:3], v[92:93], v[2:3]
	v_bfe_u32 v115, v104, 16, 1
	v_bfe_u32 v117, v1, 16, 1
	v_bfe_u32 v118, v0, 16, 1
	v_add3_u32 v88, v88, v114, s81
	v_exp_f32_e32 v96, v4
	v_exp_f32_e32 v100, v5
	v_exp_f32_e32 v97, v6
	v_add3_u32 v0, v0, v118, s81
	v_add3_u32 v1, v1, v117, s81
	v_add3_u32 v104, v104, v115, s81
	v_bfe_u32 v115, v89, 16, 1
	v_bfe_u32 v117, v2, 16, 1
	v_bfe_u32 v118, v3, 16, 1
	v_lshrrev_b32_e32 v88, 16, v88
	v_exp_f32_e64 v102, -v5
	v_exp_f32_e64 v5, -v6
	v_exp_f32_e64 v6, -v8
	v_exp_f32_e32 v8, v12
	v_add3_u32 v3, v3, v118, s81
	v_add3_u32 v2, v2, v117, s81
	v_add3_u32 v89, v89, v115, s81
	v_and_or_b32 v0, v0, s80, v88
	v_mul_lo_u32 v88, v112, s82
	v_lshrrev_b32_e32 v89, 16, v89
	v_lshrrev_b32_e32 v2, 16, v2
	v_lshrrev_b32_e32 v3, 16, v3
	v_lshl_add_u32 v88, v113, 4, v88
	v_and_or_b32 v3, v105, s80, v3
	v_and_or_b32 v2, v104, s80, v2
	v_and_or_b32 v1, v1, s80, v89
	v_add_u32_e32 v89, s26, v88
	ds_write_b128 v89, v[0:3]
	v_pk_mul_f32 v[0:1], v[10:11], v[96:97]
	v_pk_mul_f32 v[2:3], v[14:15], v[100:101]
	v_pk_mul_f32 v[10:11], v[90:91], v[108:109]
	v_pk_mul_f32 v[8:9], v[92:93], v[8:9]
	v_bfe_u32 v14, v11, 16, 1
	v_bfe_u32 v15, v10, 16, 1
	v_bfe_u32 v89, v3, 16, 1
	v_bfe_u32 v90, v2, 16, 1
	v_add3_u32 v90, v2, v90, s81
	v_add3_u32 v89, v3, v89, s81
	v_add3_u32 v2, v10, v15, s81
	v_add3_u32 v3, v11, v14, s81
	v_bfe_u32 v10, v0, 16, 1
	v_bfe_u32 v11, v1, 16, 1
	v_bfe_u32 v14, v8, 16, 1
	v_bfe_u32 v15, v9, 16, 1
	v_add3_u32 v9, v9, v15, s81
	v_add3_u32 v8, v8, v14, s81
	v_add3_u32 v1, v1, v11, s81
	v_add3_u32 v0, v0, v10, s81
	v_lshrrev_b32_e32 v0, 16, v0
	v_lshrrev_b32_e32 v1, 16, v1
	v_lshrrev_b32_e32 v8, 16, v8
	v_lshrrev_b32_e32 v9, 16, v9
	v_and_or_b32 v3, v3, s80, v9
	v_and_or_b32 v2, v2, s80, v8
	v_and_or_b32 v1, v89, s80, v1
	v_and_or_b32 v0, v90, s80, v0
	v_add_u32_e32 v8, s27, v88
	ds_write_b128 v8, v[0:3]
	v_lshlrev_b32_e32 v9, 16, v85
	v_lshlrev_b32_e32 v8, 16, v84
	v_and_b32_e32 v11, 0xffff0000, v85
	v_and_b32_e32 v10, 0xffff0000, v84
	v_and_b32_e32 v85, 0xffff0000, v87
	v_and_b32_e32 v84, 0xffff0000, v86
	v_pk_mul_f32 v[2:3], v[98:99], v[10:11]
	v_lshlrev_b32_e32 v15, 16, v87
	v_lshlrev_b32_e32 v14, 16, v86
	v_pk_mul_f32 v[86:87], v[106:107], v[84:85]
	v_pk_mul_f32 v[0:1], v[94:95], v[8:9]
	v_pk_mul_f32 v[6:7], v[6:7], v[14:15]
	v_bfe_u32 v89, v87, 16, 1
	v_bfe_u32 v90, v86, 16, 1
	v_bfe_u32 v91, v3, 16, 1
	v_bfe_u32 v92, v2, 16, 1
	v_add3_u32 v92, v2, v92, s81
	v_add3_u32 v91, v3, v91, s81
	v_add3_u32 v2, v86, v90, s81
	v_add3_u32 v3, v87, v89, s81
	v_bfe_u32 v86, v0, 16, 1
	v_bfe_u32 v87, v1, 16, 1
	v_bfe_u32 v89, v6, 16, 1
	v_bfe_u32 v90, v7, 16, 1
	v_exp_f32_e64 v4, -v4
	v_exp_f32_e64 v12, -v12
	v_add3_u32 v7, v7, v90, s81
	v_add3_u32 v6, v6, v89, s81
	v_add3_u32 v1, v1, v87, s81
	v_add3_u32 v0, v0, v86, s81
	v_lshrrev_b32_e32 v0, 16, v0
	v_lshrrev_b32_e32 v1, 16, v1
	v_lshrrev_b32_e32 v6, 16, v6
	v_lshrrev_b32_e32 v7, 16, v7
	v_add_u32_e32 v86, 0, v88
	v_and_or_b32 v3, v3, s80, v7
	v_and_or_b32 v2, v2, s80, v6
	v_and_or_b32 v1, v91, s80, v1
	v_and_or_b32 v0, v92, s80, v0
	v_add_u32_e32 v6, 0x19c00, v86
	ds_write_b128 v6, v[0:3]
	v_pk_mul_f32 v[2:3], v[102:103], v[10:11]
	v_pk_mul_f32 v[6:7], v[110:111], v[84:85]
	s_ashr_i32 s4, s3, 6
	v_pk_mul_f32 v[0:1], v[4:5], v[8:9]
	v_pk_mul_f32 v[4:5], v[12:13], v[14:15]
	v_bfe_u32 v8, v7, 16, 1
	v_bfe_u32 v9, v6, 16, 1
	v_bfe_u32 v10, v3, 16, 1
	v_bfe_u32 v11, v2, 16, 1
	v_add3_u32 v11, v2, v11, s81
	v_add3_u32 v10, v3, v10, s81
	v_add3_u32 v2, v6, v9, s81
	v_add3_u32 v3, v7, v8, s81
	v_bfe_u32 v6, v0, 16, 1
	v_bfe_u32 v7, v1, 16, 1
	v_bfe_u32 v8, v4, 16, 1
	v_bfe_u32 v9, v5, 16, 1
	s_cmpk_lt_u32 s3, 0x100
	v_add3_u32 v5, v5, v9, s81
	v_add3_u32 v4, v4, v8, s81
	v_add3_u32 v1, v1, v7, s81
	v_add3_u32 v0, v0, v6, s81
	s_cselect_b64 s[0:1], -1, 0
	v_lshrrev_b32_e32 v0, 16, v0
	v_lshrrev_b32_e32 v1, 16, v1
	v_lshrrev_b32_e32 v4, 16, v4
	v_lshrrev_b32_e32 v5, 16, v5
	s_and_b64 s[72:73], s[0:1], exec
	v_and_or_b32 v3, v3, s80, v5
	v_and_or_b32 v2, v2, s80, v4
	v_and_or_b32 v1, v10, s80, v1
	v_and_or_b32 v0, v11, s80, v0
	v_add_u32_e32 v4, 0x1c000, v86
	s_cselect_b32 s5, 0x15400, s83
	s_cselect_b32 s6, 0x19c00, s84
	s_cselect_b32 s33, 0, 0x2400
	s_lshr_b32 s72, s3, 2
	v_and_b32_e32 v116, 31, v162
	ds_write_b128 v4, v[0:3]
	s_and_b32 s72, s72, 32
	v_lshrrev_b32_e32 v0, 2, v162
	v_or_b32_e32 v96, s72, v116
	v_and_b32_e32 v97, 8, v0
	s_add_i32 s5, s5, 0
	v_mad_u32_u24 v0, v96, s85, v97
	s_waitcnt lgkmcnt(0)
	s_barrier
; #define LAS __attribute__((address_space(3)))
; __device__ __forceinline__ unsigned f2bf(float f) { unsigned u = __builtin_bit_cast(unsigned, f); return (u + 0x7fffu + ((u >> 16) & 1u)) >> 16; }
; __device__ __forceinline__ int crow(int r, int hi) { return (r & 3) + 8 * (r >> 2) + 4 * hi; }
; #define LBAR() do { asm volatile("s_waitcnt lgkmcnt(0)" ::: "memory"); __builtin_amdgcn_s_barrier(); asm volatile("" ::: "memory"); } while (0)
; __device__ __forceinline__ void g3_unit(const GPre& R, const float* __restrict__ gng, bf16* __restrict__ MIXIN, int n, int h, LAS char* lds) {
;     ...
;   { const int dir = wid >> 2, ct = (wid >> 1) & 1, st = wid & 1; f32x16 acc = {};
;     lcp Q = lds + (dir ? L_QTB : L_QTF); lcp K = lds + (dir ? L_KTB : L_KTF);
; #pragma unroll
;     for (int ks = 0; ks < 4; ++ks) acc = __builtin_amdgcn_mfma_f32_32x32x16_bf16(frag(Q, 32 * ct, 16 * ks, lane), frag(K, 32 * st, 16 * ks, lane), acc, 0, 0, 0);
;     LAS bf16* ATT = (LAS bf16*)(lds + (dir ? L_ATTB : L_ATTF));
; #pragma unroll
;     for (int r = 0; r < 16; ++r) { const int c = 32 * ct + crow(r, hi), s_ = 32 * st + r32; const bool keep = dir ? (s_ > c) : (s_ <= c);
;       ATT[c * ST72 + s_] = (bf16)f2bf(keep ? acc[r] : 0.f); } }
;   LBAR();
	v_lshl_add_u32 v0, v0, 1, s5
	s_lshl_b32 s73, s4, 5
	ds_read_b128 v[0:3], v0
	v_and_or_b32 v98, s73, 32, v116
	s_add_i32 s6, s6, 0
	v_mad_u32_u24 v4, v98, s85, v97
	v_lshl_add_u32 v4, v4, 1, s6
	ds_read_b128 v[4:7], v4
	v_or_b32_e32 v88, 16, v97
	v_mad_u32_u24 v8, v96, s85, v88
	v_lshl_add_u32 v8, v8, 1, s5
	v_mad_u32_u24 v88, v98, s85, v88
	ds_read_b128 v[84:87], v8
	v_lshl_add_u32 v88, v88, 1, s6
	ds_read_b128 v[88:91], v88
	s_waitcnt lgkmcnt(2)
	v_mfma_f32_32x32x16_bf16 v[0:15], v[0:3], v[4:7], 0
	v_or_b32_e32 v99, 32, v97
	v_mad_u32_u24 v92, v96, s85, v99
	v_lshl_add_u32 v92, v92, 1, s5
	ds_read_b128 v[92:95], v92
	v_or_b32_e32 v97, 48, v97
	v_bfe_u32 v118, v162, 5, 1
	v_lshlrev_b32_e32 v117, 2, v118
	s_waitcnt lgkmcnt(1)
	v_mfma_f32_32x32x16_bf16 v[0:15], v[84:87], v[88:91], v[0:15]
	v_mad_u32_u24 v84, v98, s85, v99
	v_lshl_add_u32 v84, v84, 1, s6
	ds_read_b128 v[84:87], v84
	v_mad_u32_u24 v88, v96, s85, v97
	v_lshl_add_u32 v88, v88, 1, s5
	ds_read_b128 v[88:91], v88
	s_add_i32 s5, s33, 0
	s_waitcnt lgkmcnt(1)
	v_mfma_f32_32x32x16_bf16 v[0:15], v[92:95], v[84:87], v[0:15]
	v_mad_u32_u24 v84, v98, s85, v97
	v_lshl_add_u32 v84, v84, 1, s6
	ds_read_b128 v[84:87], v84
	s_and_b32 s6, s73, 0x60
	v_and_b32_e32 v100, 63, v162
	v_bfe_u32 v124, v100, 2, 2
	s_waitcnt lgkmcnt(0)
	v_mfma_f32_32x32x16_bf16 v[0:15], v[88:91], v[84:87], v[0:15]
	v_or_b32_e32 v84, s72, v117
	v_cmp_gt_u32_e32 vcc, v98, v84
	s_xor_b64 vcc, s[0:1], vcc
	v_lshlrev_b32_e32 v85, 1, v98
	s_nop 7
	v_cndmask_b32_e32 v0, 0, v0, vcc
	v_bfe_u32 v86, v0, 16, 1
	v_add3_u32 v0, v0, v86, s81
	v_mul_u32_u24_e32 v86, 0x90, v84
	v_add3_u32 v85, s5, v85, v86
	ds_write_b16_d16_hi v85, v0
	v_or_b32_e32 v0, 1, v84
	v_cmp_gt_u32_e32 vcc, v98, v0
	s_xor_b64 vcc, s[0:1], vcc
	s_ashr_i32 s5, s3, 8
	v_cndmask_b32_e32 v0, 0, v1, vcc
	v_bfe_u32 v1, v0, 16, 1
	v_add3_u32 v0, v0, v1, s81
	ds_write_b16_d16_hi v85, v0 offset:144
	v_or_b32_e32 v0, 2, v84
	v_cmp_gt_u32_e32 vcc, v98, v0
	s_xor_b64 vcc, s[0:1], vcc
	s_lshl_b32 s3, s5, 5
	v_cndmask_b32_e32 v0, 0, v2, vcc
	v_bfe_u32 v1, v0, 16, 1
	v_add3_u32 v0, v0, v1, s81
	ds_write_b16_d16_hi v85, v0 offset:288
	v_or_b32_e32 v0, 3, v84
	v_cmp_gt_u32_e32 vcc, v98, v0
	s_xor_b64 vcc, s[0:1], vcc
	s_nop 0
	v_cndmask_b32_e32 v0, 0, v3, vcc
	v_bfe_u32 v1, v0, 16, 1
	v_add3_u32 v0, v0, v1, s81
	ds_write_b16_d16_hi v85, v0 offset:432
	v_or_b32_e32 v0, 8, v84
	v_cmp_gt_u32_e32 vcc, v98, v0
	s_xor_b64 vcc, s[0:1], vcc
	s_nop 0
	v_cndmask_b32_e32 v0, 0, v4, vcc
	v_bfe_u32 v1, v0, 16, 1
	v_add3_u32 v0, v0, v1, s81
	ds_write_b16_d16_hi v85, v0 offset:1152
	v_or_b32_e32 v0, 9, v84
	v_cmp_gt_u32_e32 vcc, v98, v0
	s_xor_b64 vcc, s[0:1], vcc
	v_bfe_u32 v4, v162, 2, 4
	v_cndmask_b32_e32 v0, 0, v5, vcc
	v_bfe_u32 v1, v0, 16, 1
	v_add3_u32 v0, v0, v1, s81
	ds_write_b16_d16_hi v85, v0 offset:1296
	v_or_b32_e32 v0, 10, v84
	v_cmp_gt_u32_e32 vcc, v98, v0
	s_xor_b64 vcc, s[0:1], vcc
	v_and_b32_e32 v120, 8, v4
	v_cndmask_b32_e32 v0, 0, v6, vcc
	v_bfe_u32 v1, v0, 16, 1
	v_add3_u32 v0, v0, v1, s81
	ds_write_b16_d16_hi v85, v0 offset:1440
	v_or_b32_e32 v0, 11, v84
	v_cmp_gt_u32_e32 vcc, v98, v0
	s_xor_b64 vcc, s[0:1], vcc
	v_and_b32_e32 v133, 11, v4
	v_cndmask_b32_e32 v0, 0, v7, vcc
	v_bfe_u32 v1, v0, 16, 1
	v_add3_u32 v0, v0, v1, s81
	ds_write_b16_d16_hi v85, v0 offset:1584
	v_or_b32_e32 v0, 16, v84
	v_cmp_gt_u32_e32 vcc, v98, v0
	s_xor_b64 vcc, s[0:1], vcc
	v_or_b32_e32 v104, 16, v120
	v_cndmask_b32_e32 v0, 0, v8, vcc
	v_bfe_u32 v1, v0, 16, 1
	v_add3_u32 v0, v0, v1, s81
	ds_write_b16_d16_hi v85, v0 offset:2304
	v_or_b32_e32 v0, 17, v84
	v_cmp_gt_u32_e32 vcc, v98, v0
	s_xor_b64 vcc, s[0:1], vcc
	v_or_b32_e32 v135, v104, v124
	v_cndmask_b32_e32 v0, 0, v9, vcc
	v_bfe_u32 v1, v0, 16, 1
	v_add3_u32 v0, v0, v1, s81
	ds_write_b16_d16_hi v85, v0 offset:2448
	v_or_b32_e32 v0, 18, v84
	v_cmp_gt_u32_e32 vcc, v98, v0
	s_xor_b64 vcc, s[0:1], vcc
	v_or_b32_e32 v112, 32, v120
	v_cndmask_b32_e32 v0, 0, v10, vcc
	v_bfe_u32 v1, v0, 16, 1
	v_add3_u32 v0, v0, v1, s81
	ds_write_b16_d16_hi v85, v0 offset:2592
	v_or_b32_e32 v0, 19, v84
	v_cmp_gt_u32_e32 vcc, v98, v0
	s_xor_b64 vcc, s[0:1], vcc
	v_or_b32_e32 v137, v112, v124
	v_cndmask_b32_e32 v0, 0, v11, vcc
	v_bfe_u32 v1, v0, 16, 1
	v_add3_u32 v0, v0, v1, s81
	ds_write_b16_d16_hi v85, v0 offset:2736
	v_or_b32_e32 v0, 24, v84
	v_cmp_gt_u32_e32 vcc, v98, v0
	s_xor_b64 vcc, s[0:1], vcc
	v_or_b32_e32 v125, 48, v120
	v_cndmask_b32_e32 v0, 0, v12, vcc
	v_bfe_u32 v1, v0, 16, 1
	v_add3_u32 v0, v0, v1, s81
	ds_write_b16_d16_hi v85, v0 offset:3456
	v_or_b32_e32 v0, 25, v84
	v_cmp_gt_u32_e32 vcc, v98, v0
	s_xor_b64 vcc, s[0:1], vcc
	v_or_b32_e32 v138, v125, v124
	v_cndmask_b32_e32 v0, 0, v13, vcc
	v_bfe_u32 v1, v0, 16, 1
	v_add3_u32 v0, v0, v1, s81
	ds_write_b16_d16_hi v85, v0 offset:3600
	v_or_b32_e32 v0, 26, v84
	v_cmp_gt_u32_e32 vcc, v98, v0
	s_xor_b64 vcc, s[0:1], vcc
	s_nop 0
	v_cndmask_b32_e32 v0, 0, v14, vcc
	v_bfe_u32 v1, v0, 16, 1
	v_add3_u32 v0, v0, v1, s81
	ds_write_b16_d16_hi v85, v0 offset:3744
	v_or_b32_e32 v0, 27, v84
	v_cmp_gt_u32_e32 vcc, v98, v0
	s_xor_b64 vcc, s[0:1], vcc
	s_nop 0
	v_cndmask_b32_e32 v0, 0, v15, vcc
	v_bfe_u32 v1, v0, 16, 1
	v_add3_u32 v0, v0, v1, s81
	ds_write_b16_d16_hi v85, v0 offset:3888
	v_or_b32_e32 v0, s3, v116
	v_mul_lo_u32 v119, v0, s85
	v_lshlrev_b32_e32 v1, 2, v162
	v_and_b32_e32 v0, 16, v162
	v_and_b32_e32 v1, 12, v1
	v_add_lshl_u32 v128, v119, v120, 1
	s_waitcnt lgkmcnt(0)
	s_barrier
; #define LAS __attribute__((address_space(3)))
; __device__ __forceinline__ void g3_unit(const GPre& R, const float* __restrict__ gng, bf16* __restrict__ MIXIN, int n, int h, LAS char* lds) {
;     ...
;   { const int ct = wid >> 2, et = wid & 3; f32x16 acc = {};
; #pragma unroll
;     for (int dir = 0; dir < 2; ++dir) { lcp ATT = lds + (dir ? L_ATTB : L_ATTF); lcp Q = lds + (dir ? L_QTB : L_QTF); lcp S = lds + (dir ? L_SB : L_SF);
; #pragma unroll
;       for (int ks = 0; ks < 4; ++ks) { acc = __builtin_amdgcn_mfma_f32_32x32x16_bf16(frag(ATT, 32 * ct, 16 * ks, lane), trfrag(lds + L_V, VS, 16 * ks, 32 * et, lane), acc, 0, 0, 0);
;                                        acc = __builtin_amdgcn_mfma_f32_32x32x16_bf16(frag(Q, 32 * ct, 16 * ks, lane), trfrag(S, VS, 16 * ks, 32 * et, lane), acc, 0, 0, 0); } }
;     LAS float* RS = (LAS float*)(lds + L_RS);
;     float ssr[16];
; #pragma unroll
;     for (int r = 0; r < 16; ++r) { float ss = acc[r] * acc[r]; ss += __shfl_xor(ss, 1); ss += __shfl_xor(ss, 2); ss += __shfl_xor(ss, 4); ss += __shfl_xor(ss, 8); ss += __shfl_xor(ss, 16); ssr[r] = ss; }
	v_or3_b32 v0, v1, v0, s6
	v_add_u32_e32 v5, 0, v128
	v_lshl_add_u32 v132, v0, 1, 0
	ds_read_b128 v[0:3], v5
	v_mad_u32_u24 v4, v133, s58, v132
	ds_read_b64_tr_b16 v[84:85], v4 offset:34816
	ds_read_b64_tr_b16 v[86:87], v4 offset:35904
	ds_read_b64_tr_b16 v[88:89], v4 offset:52224
	ds_read_b64_tr_b16 v[90:91], v4 offset:53312
	ds_read_b128 v[92:95], v5 offset:9216
	v_add_u32_e32 v96, s26, v128
	ds_read_b128 v[96:99], v96
	s_waitcnt lgkmcnt(4)
	v_mfma_f32_32x32x16_bf16 v[0:15], v[0:3], v[84:87], 0
	v_add_lshl_u32 v134, v119, v104, 1
	v_add_u32_e32 v105, 0, v134
	ds_read_b128 v[100:103], v105
	v_add_lshl_u32 v136, v119, v112, 1
	v_add_u32_e32 v113, 0, v136
	v_add_lshl_u32 v119, v119, v125, 1
	v_add_u32_e32 v126, 0, v119
	s_waitcnt lgkmcnt(1)
	v_mfma_f32_32x32x16_bf16 v[0:15], v[96:99], v[88:91], v[0:15]
	v_mad_u32_u24 v98, v135, s58, v132
	ds_read_b64_tr_b16 v[88:89], v98 offset:34816
	ds_read_b64_tr_b16 v[90:91], v98 offset:35904
	ds_read_b64_tr_b16 v[96:97], v98 offset:52224
	ds_read_b64_tr_b16 v[98:99], v98 offset:53312
	ds_read_b128 v[104:107], v105 offset:9216
	ds_read_b128 v[108:111], v113
	v_add_u32_e32 v128, s27, v128
	v_cmp_lt_i32_e32 vcc, v252, v213
	s_waitcnt lgkmcnt(4)
	v_mfma_f32_32x32x16_bf16 v[0:15], v[100:103], v[88:91], v[0:15]
	v_add_u32_e32 v100, s26, v134
	ds_read_b128 v[100:103], v100
	s_waitcnt lgkmcnt(0)
	v_mfma_f32_32x32x16_bf16 v[0:15], v[100:103], v[96:99], v[0:15]
	v_mad_u32_u24 v102, v137, s58, v132
	ds_read_b64_tr_b16 v[96:97], v102 offset:34816
	ds_read_b64_tr_b16 v[98:99], v102 offset:35904
	ds_read_b64_tr_b16 v[100:101], v102 offset:52224
	ds_read_b64_tr_b16 v[102:103], v102 offset:53312
	ds_read_b128 v[112:115], v113 offset:9216
	ds_read_b128 v[120:123], v126
	s_waitcnt lgkmcnt(4)
	v_mfma_f32_32x32x16_bf16 v[0:15], v[108:111], v[96:99], v[0:15]
	v_add_u32_e32 v108, s26, v136
	ds_read_b128 v[108:111], v108
	s_waitcnt lgkmcnt(0)
	v_mfma_f32_32x32x16_bf16 v[0:15], v[108:111], v[100:103], v[0:15]
	v_mad_u32_u24 v110, v138, s58, v132
	ds_read_b64_tr_b16 v[100:101], v110 offset:34816
	ds_read_b64_tr_b16 v[102:103], v110 offset:35904
	ds_read_b64_tr_b16 v[108:109], v110 offset:52224
	ds_read_b64_tr_b16 v[110:111], v110 offset:53312
	ds_read_b128 v[124:127], v126 offset:9216
	ds_read_b128 v[128:131], v128
	s_waitcnt lgkmcnt(4)
	v_mfma_f32_32x32x16_bf16 v[0:15], v[120:123], v[100:103], v[0:15]
	v_add_u32_e32 v120, s26, v119
	ds_read_b128 v[120:123], v120
	s_waitcnt lgkmcnt(0)
	v_mfma_f32_32x32x16_bf16 v[0:15], v[120:123], v[108:111], v[0:15]
	v_add_u32_e32 v108, 0x11000, v132
	v_mfma_f32_32x32x16_bf16 v[0:15], v[92:95], v[84:87], v[0:15]
	v_mad_u32_u24 v86, v133, s58, v108
	ds_read_b64_tr_b16 v[84:85], v86
	ds_read_b64_tr_b16 v[86:87], v86 offset:1088
	v_add_u32_e32 v92, s27, v136
	s_waitcnt lgkmcnt(0)
	v_mfma_f32_32x32x16_bf16 v[0:15], v[128:131], v[84:87], v[0:15]
	v_add_u32_e32 v84, s27, v134
	ds_read_b128 v[84:87], v84
	v_mfma_f32_32x32x16_bf16 v[0:15], v[104:107], v[88:91], v[0:15]
	v_mad_u32_u24 v90, v135, s58, v108
	ds_read_b64_tr_b16 v[88:89], v90
	ds_read_b64_tr_b16 v[90:91], v90 offset:1088
	ds_read_b128 v[92:95], v92
	s_waitcnt lgkmcnt(1)
	v_mfma_f32_32x32x16_bf16 v[0:15], v[84:87], v[88:91], v[0:15]
	v_mad_u32_u24 v86, v137, s58, v108
	ds_read_b64_tr_b16 v[84:85], v86
	ds_read_b64_tr_b16 v[86:87], v86 offset:1088
	v_mad_u32_u24 v90, v138, s58, v108
	v_mfma_f32_32x32x16_bf16 v[0:15], v[112:115], v[96:99], v[0:15]
	s_waitcnt lgkmcnt(0)
	v_mfma_f32_32x32x16_bf16 v[0:15], v[92:95], v[84:87], v[0:15]
	v_add_u32_e32 v84, s27, v119
	ds_read_b128 v[84:87], v84
	ds_read_b64_tr_b16 v[88:89], v90
	ds_read_b64_tr_b16 v[90:91], v90 offset:1088
	v_mfma_f32_32x32x16_bf16 v[0:15], v[124:127], v[100:103], v[0:15]
	s_waitcnt lgkmcnt(0)
	v_mfma_f32_32x32x16_bf16 v[0:15], v[84:87], v[88:91], v[0:15]
	v_cndmask_b32_e32 v84, v211, v252, vcc
	v_lshlrev_b32_e32 v112, 2, v84
	v_cmp_lt_i32_e32 vcc, v253, v213
	s_nop 1
	v_cndmask_b32_e32 v84, v211, v253, vcc
	v_lshlrev_b32_e32 v119, 2, v84
	s_nop 4
	v_pk_mul_f32 v[88:89], v[2:3], v[2:3]
	ds_bpermute_b32 v88, v112, v88
	ds_bpermute_b32 v89, v112, v89
	v_cmp_lt_i32_e32 vcc, v254, v213
	v_pk_mul_f32 v[98:99], v[4:5], v[4:5]
	ds_bpermute_b32 v98, v112, v98
	v_cndmask_b32_e32 v84, v211, v254, vcc
	s_waitcnt lgkmcnt(1)
	v_pk_fma_f32 v[88:89], v[2:3], v[2:3], v[88:89]
	ds_bpermute_b32 v92, v119, v88
	ds_bpermute_b32 v93, v119, v89
	v_lshlrev_b32_e32 v122, 2, v84
	ds_bpermute_b32 v99, v112, v99
	v_cmp_lt_i32_e32 vcc, v212, v213
	v_pk_mul_f32 v[90:91], v[6:7], v[6:7]
	s_waitcnt lgkmcnt(1)
	v_pk_add_f32 v[88:89], v[88:89], v[92:93]
	ds_bpermute_b32 v92, v122, v88
	ds_bpermute_b32 v93, v122, v89
	v_cndmask_b32_e32 v84, v211, v212, vcc
	v_lshlrev_b32_e32 v123, 2, v84
	s_waitcnt lgkmcnt(2)
	v_pk_fma_f32 v[98:99], v[4:5], v[4:5], v[98:99]
	ds_bpermute_b32 v100, v119, v98
	s_waitcnt lgkmcnt(1)
	v_pk_add_f32 v[88:89], v[88:89], v[92:93]
	ds_bpermute_b32 v92, v123, v88
	ds_bpermute_b32 v93, v123, v89
	ds_bpermute_b32 v101, v119, v99
	v_pk_mul_f32 v[94:95], v[8:9], v[8:9]
	v_pk_mul_f32 v[96:97], v[10:11], v[10:11]
	ds_bpermute_b32 v110, v112, v96
	s_waitcnt lgkmcnt(2)
	v_pk_add_f32 v[88:89], v[88:89], v[92:93]
	ds_bpermute_b32 v92, v112, v90
	ds_bpermute_b32 v93, v112, v91
	s_waitcnt lgkmcnt(3)
; __device__ __forceinline__ int crow(int r, int hi) { return (r & 3) + 8 * (r >> 2) + 4 * hi; }
; #define LBAR() do { asm volatile("s_waitcnt lgkmcnt(0)" ::: "memory"); __builtin_amdgcn_s_barrier(); asm volatile("" ::: "memory"); } while (0)
; __device__ __forceinline__ void g3_unit(const GPre& R, const float* __restrict__ gng, bf16* __restrict__ MIXIN, int n, int h, LAS char* lds) {
;     ...
;     for (int r = 0; r < 16; ++r) { float ss = acc[r] * acc[r]; ss += __shfl_xor(ss, 1); ss += __shfl_xor(ss, 2); ss += __shfl_xor(ss, 4); ss += __shfl_xor(ss, 8); ss += __shfl_xor(ss, 16); ssr[r] = ss; }
;     if (r32 == 0) {
; #pragma unroll
;       for (int r = 0; r < 16; ++r) RS[wid * 32 + crow(r, hi)] = ssr[r]; }
;     LBAR();
	v_pk_add_f32 v[98:99], v[98:99], v[100:101]
	ds_bpermute_b32 v100, v122, v98
	ds_bpermute_b32 v101, v122, v99
	ds_bpermute_b32 v111, v112, v97
	s_waitcnt lgkmcnt(3)
	v_pk_fma_f32 v[92:93], v[6:7], v[6:7], v[92:93]
	ds_bpermute_b32 v102, v119, v92
	ds_bpermute_b32 v103, v119, v93
	s_waitcnt lgkmcnt(3)
	v_pk_add_f32 v[98:99], v[98:99], v[100:101]
	ds_bpermute_b32 v100, v123, v98
	ds_bpermute_b32 v101, v123, v99
	v_pk_mul_f32 v[84:85], v[0:1], v[0:1]
	s_waitcnt lgkmcnt(2)
	v_pk_add_f32 v[102:103], v[92:93], v[102:103]
	ds_bpermute_b32 v108, v122, v102
	ds_bpermute_b32 v109, v122, v103
	s_waitcnt lgkmcnt(2)
	v_pk_add_f32 v[92:93], v[98:99], v[100:101]
	ds_bpermute_b32 v98, v112, v94
	ds_bpermute_b32 v99, v112, v95
	v_pk_mul_f32 v[104:105], v[14:15], v[14:15]
	s_waitcnt lgkmcnt(2)
	v_pk_add_f32 v[100:101], v[102:103], v[108:109]
	ds_bpermute_b32 v102, v123, v100
	ds_bpermute_b32 v103, v123, v101
	s_waitcnt lgkmcnt(2)
	v_pk_fma_f32 v[98:99], v[8:9], v[8:9], v[98:99]
	ds_bpermute_b32 v108, v119, v98
	ds_bpermute_b32 v109, v119, v99
	v_pk_mul_f32 v[106:107], v[12:13], v[12:13]
	s_waitcnt lgkmcnt(2)
	v_pk_add_f32 v[96:97], v[100:101], v[102:103]
	ds_bpermute_b32 v84, v112, v84
	ds_bpermute_b32 v85, v112, v85
	s_waitcnt lgkmcnt(2)
	v_pk_add_f32 v[100:101], v[98:99], v[108:109]
	v_pk_fma_f32 v[108:109], v[10:11], v[10:11], v[110:111]
	ds_bpermute_b32 v110, v119, v108
	ds_bpermute_b32 v111, v119, v109
	ds_bpermute_b32 v106, v112, v106
	ds_bpermute_b32 v107, v112, v107
	ds_bpermute_b32 v104, v112, v104
	ds_bpermute_b32 v105, v112, v105
	s_waitcnt lgkmcnt(4)
	v_pk_add_f32 v[108:109], v[108:109], v[110:111]
	ds_bpermute_b32 v110, v122, v108
	ds_bpermute_b32 v111, v122, v109
	v_cmp_lt_i32_e32 vcc, v218, v213
	v_pk_fma_f32 v[84:85], v[0:1], v[0:1], v[84:85]
	s_waitcnt lgkmcnt(4)
	v_pk_fma_f32 v[106:107], v[12:13], v[12:13], v[106:107]
	v_cndmask_b32_e32 v86, v211, v218, vcc
	s_waitcnt lgkmcnt(0)
	v_pk_add_f32 v[108:109], v[108:109], v[110:111]
	v_pk_fma_f32 v[114:115], v[14:15], v[14:15], v[104:105]
	v_lshlrev_b32_e32 v124, 2, v86
	ds_bpermute_b32 v86, v119, v84
	ds_bpermute_b32 v87, v119, v85
	ds_bpermute_b32 v110, v123, v108
	ds_bpermute_b32 v111, v123, v109
	ds_bpermute_b32 v112, v119, v106
	ds_bpermute_b32 v113, v119, v107
	ds_bpermute_b32 v120, v119, v114
	ds_bpermute_b32 v121, v119, v115
	s_waitcnt lgkmcnt(6)
	v_pk_add_f32 v[84:85], v[84:85], v[86:87]
	s_waitcnt lgkmcnt(4)
	v_pk_add_f32 v[104:105], v[108:109], v[110:111]
	s_waitcnt lgkmcnt(2)
	v_pk_add_f32 v[108:109], v[106:107], v[112:113]
	ds_bpermute_b32 v86, v122, v84
	s_waitcnt lgkmcnt(1)
	v_pk_add_f32 v[112:113], v[114:115], v[120:121]
	ds_bpermute_b32 v87, v122, v85
	ds_bpermute_b32 v102, v122, v100
	ds_bpermute_b32 v103, v122, v101
	ds_bpermute_b32 v110, v122, v108
	ds_bpermute_b32 v111, v122, v109
	ds_bpermute_b32 v114, v122, v112
	ds_bpermute_b32 v115, v122, v113
	s_waitcnt lgkmcnt(6)
	v_pk_add_f32 v[84:85], v[84:85], v[86:87]
	s_waitcnt lgkmcnt(4)
	v_pk_add_f32 v[100:101], v[100:101], v[102:103]
	s_waitcnt lgkmcnt(2)
	v_pk_add_f32 v[108:109], v[108:109], v[110:111]
	ds_bpermute_b32 v86, v123, v84
	s_waitcnt lgkmcnt(1)
	v_pk_add_f32 v[112:113], v[112:113], v[114:115]
	ds_bpermute_b32 v87, v123, v85
	ds_bpermute_b32 v102, v123, v100
	ds_bpermute_b32 v103, v123, v101
	ds_bpermute_b32 v110, v123, v108
	ds_bpermute_b32 v111, v123, v109
	ds_bpermute_b32 v114, v123, v112
	ds_bpermute_b32 v115, v123, v113
	s_waitcnt lgkmcnt(6)
	v_pk_add_f32 v[84:85], v[84:85], v[86:87]
	s_waitcnt lgkmcnt(4)
	v_pk_add_f32 v[100:101], v[100:101], v[102:103]
	s_waitcnt lgkmcnt(2)
	v_pk_add_f32 v[108:109], v[108:109], v[110:111]
	ds_bpermute_b32 v86, v124, v84
	s_waitcnt lgkmcnt(1)
	v_pk_add_f32 v[112:113], v[112:113], v[114:115]
	ds_bpermute_b32 v87, v124, v85
	ds_bpermute_b32 v90, v124, v88
	ds_bpermute_b32 v91, v124, v89
	ds_bpermute_b32 v94, v124, v92
	ds_bpermute_b32 v95, v124, v93
	ds_bpermute_b32 v98, v124, v96
	ds_bpermute_b32 v99, v124, v97
	ds_bpermute_b32 v102, v124, v100
	ds_bpermute_b32 v103, v124, v101
	ds_bpermute_b32 v106, v124, v104
	ds_bpermute_b32 v107, v124, v105
	ds_bpermute_b32 v110, v124, v108
	ds_bpermute_b32 v111, v124, v109
	ds_bpermute_b32 v114, v124, v112
	ds_bpermute_b32 v115, v124, v113
	v_cmp_eq_u32_e32 vcc, 0, v116
	s_and_saveexec_b64 s[0:1], vcc
	s_cbranch_execz .LBB0_407
	s_lshl_b32 s4, s4, 7
	s_add_i32 s4, s4, 0
	v_lshl_add_u32 v118, v118, 4, s4
	v_add_u32_e32 v118, 0x1e400, v118
	s_waitcnt lgkmcnt(14)
	v_pk_add_f32 v[84:85], v[84:85], v[86:87]
	s_waitcnt lgkmcnt(12)
	v_pk_add_f32 v[86:87], v[88:89], v[90:91]
	ds_write_b128 v118, v[84:87]
	s_waitcnt lgkmcnt(11)
	v_pk_add_f32 v[84:85], v[92:93], v[94:95]
	s_waitcnt lgkmcnt(9)
	v_pk_add_f32 v[86:87], v[96:97], v[98:99]
	ds_write_b128 v118, v[84:87] offset:32
	s_waitcnt lgkmcnt(8)
	v_pk_add_f32 v[84:85], v[100:101], v[102:103]
	s_waitcnt lgkmcnt(6)
	v_pk_add_f32 v[86:87], v[104:105], v[106:107]
	ds_write_b128 v118, v[84:87] offset:64
	s_waitcnt lgkmcnt(5)
	v_pk_add_f32 v[84:85], v[108:109], v[110:111]
	s_waitcnt lgkmcnt(3)
	v_pk_add_f32 v[86:87], v[112:113], v[114:115]
	ds_write_b128 v118, v[84:87] offset:96
	s_branch .LBB0_407
